# lighter LDS-DMA sequence (M0 values precomputed in SGPRs stashed via v255 lanes) for the up-projection GEMM
# speedup vs baseline: 1.0020x; 1.0020x over previous
; DI void load_rstd(float (&rs)[4], const float* ssq, int row0, int lr) {
; #pragma unroll
;   for (int mt = 0; mt < 4; ++mt) {
;     const float4* q = (const float4*)(ssq + (size_t)(row0 + mt * 16 + lr) * 16);
;     const float4 a = q[0], b = q[1], c = q[2], d = q[3];
;     const float s = ((a.x + a.y) + (a.z + a.w)) + ((b.x + b.y) + (b.z + b.w)) + ((c.x + c.y) + (c.z + c.w)) + ((d.x + d.y) + (d.z + d.w));
;     rs[mt] = rsqrtf(s * (1.0f / 1024.0f) + EPS);
;   }
; }
.LBB0_1313:
	s_ashr_i32 s4, s2, 9
	s_lshr_b32 s1, s4, 30
	s_add_i32 s1, s4, s1
	s_ashr_i32 s5, s1, 2
	s_lshl_b32 s1, s5, 6
	s_and_b32 s6, s12, 56
	s_lshl_b32 s5, s5, 5
	s_lshl_b32 s4, s4, 3
	s_or_b32 s1, s1, s6
	s_bfe_u32 s6, s2, 0x30003
	s_sub_i32 s4, s4, s5
	s_bfe_u32 s5, s2, 0x30006
	s_or_b32 s1, s1, s6
	s_or_b32 s4, s4, s5
	s_cmpk_lt_i32 s1, 0x80
	s_cselect_b64 s[6:7], -1, 0
	s_cmp_lt_i32 s4, 32
	s_cselect_b64 s[8:9], -1, 0
	s_and_b64 s[6:7], s[6:7], s[8:9]
	s_andn2_b64 vcc, exec, s[6:7]
	s_cbranch_vccnz .LBB0_1312
	s_lshl_b32 s8, s1, 7
	v_add_u32_e32 v102, s8, v125
	v_ashrrev_i32_e32 v103, 31, v102
	v_readlane_b32 s14, v254, 41
	v_lshlrev_b64 v[0:1], 6, v[102:103]
	v_readlane_b32 s15, v254, 42
	v_or_b32_e32 v98, 16, v102
	v_ashrrev_i32_e32 v99, 31, v98
	v_lshl_add_u64 v[12:13], s[14:15], 0, v[0:1]
	global_load_dwordx4 v[0:3], v[12:13], off offset:32
	global_load_dwordx4 v[4:7], v[12:13], off offset:16
	global_load_dwordx4 v[8:11], v[12:13], off
	s_nop 0
	global_load_dwordx4 v[12:15], v[12:13], off offset:48
	s_lshl_b32 s6, s4, 7
	s_mov_b32 s4, 0x358637bd
	s_mov_b32 s16, 0x3a800000
	s_mov_b32 s1, 0x800000
	v_or_b32_e32 v106, 32, v102
	v_ashrrev_i32_e32 v107, 31, v106
	v_or_b32_e32 v104, 48, v102
	v_ashrrev_i32_e32 v105, 31, v104
	s_ashr_i32 s9, s8, 31
	s_waitcnt vmcnt(7)
	v_mov_b32_e32 v72, v148
	v_or_b32_e32 v100, s6, v124
	s_waitcnt vmcnt(2)
	v_mov_b32_e32 v18, v5
	s_waitcnt vmcnt(1)
	v_mov_b32_e32 v16, v9
	v_mov_b32_e32 v17, v10
	v_mov_b32_e32 v19, v6
	v_mov_b32_e32 v9, v11
	v_mov_b32_e32 v5, v7
	v_mov_b32_e32 v6, v1
	v_pk_add_f32 v[8:9], v[16:17], v[8:9]
	v_pk_add_f32 v[4:5], v[18:19], v[4:5]
	v_pk_add_f32 v[0:1], v[0:1], v[6:7]
	v_mov_b32_e32 v6, v3
	v_pk_add_f32 v[8:9], v[8:9], v[8:9] op_sel:[0,1] op_sel_hi:[1,0]
	v_pk_add_f32 v[4:5], v[4:5], v[4:5] op_sel:[0,1] op_sel_hi:[1,0]
	v_pk_add_f32 v[2:3], v[2:3], v[6:7]
	s_waitcnt vmcnt(0)
	v_mov_b32_e32 v9, v12
	v_mov_b32_e32 v5, v13
	v_mov_b32_e32 v1, v14
	v_mov_b32_e32 v3, v15
	v_pk_add_f32 v[4:5], v[8:9], v[4:5]
	v_pk_add_f32 v[0:1], v[0:1], v[2:3]
	s_nop 0
	v_pk_add_f32 v[16:17], v[4:5], v[0:1]
	v_lshlrev_b64 v[0:1], 6, v[98:99]
	v_lshl_add_u64 v[12:13], s[14:15], 0, v[0:1]
	global_load_dwordx4 v[0:3], v[12:13], off offset:32
	global_load_dwordx4 v[4:7], v[12:13], off offset:16
	global_load_dwordx4 v[8:11], v[12:13], off
	s_nop 0
	global_load_dwordx4 v[12:15], v[12:13], off offset:48
	s_waitcnt vmcnt(2)
	v_mov_b32_e32 v20, v5
	s_waitcnt vmcnt(1)
	v_mov_b32_e32 v18, v9
	v_mov_b32_e32 v19, v10
	v_mov_b32_e32 v21, v6
	v_mov_b32_e32 v9, v11
	v_mov_b32_e32 v5, v7
	v_mov_b32_e32 v6, v1
	v_pk_add_f32 v[8:9], v[18:19], v[8:9]
	v_pk_add_f32 v[4:5], v[20:21], v[4:5]
	v_pk_add_f32 v[0:1], v[0:1], v[6:7]
	v_mov_b32_e32 v6, v3
	v_pk_add_f32 v[8:9], v[8:9], v[8:9] op_sel:[0,1] op_sel_hi:[1,0]
	v_pk_add_f32 v[4:5], v[4:5], v[4:5] op_sel:[0,1] op_sel_hi:[1,0]
	v_pk_add_f32 v[2:3], v[2:3], v[6:7]
	s_waitcnt vmcnt(0)
	v_mov_b32_e32 v9, v12
	v_mov_b32_e32 v5, v13
	v_mov_b32_e32 v1, v14
	v_mov_b32_e32 v3, v15
	v_pk_add_f32 v[4:5], v[8:9], v[4:5]
	v_pk_add_f32 v[0:1], v[0:1], v[2:3]
	v_mov_b32_e32 v3, v16
	v_pk_add_f32 v[0:1], v[4:5], v[0:1]
	s_nop 0
	v_mov_b32_e32 v2, v0
	v_mov_b32_e32 v16, v1
	v_pk_add_f32 v[2:3], v[2:3], v[16:17]
	v_mov_b64_e32 v[0:1], s[4:5]
	v_pk_fma_f32 v[2:3], v[2:3], s[16:17], v[0:1] op_sel_hi:[1,0,0]
	s_nop 0
	v_mul_f32_e32 v4, 0x4b800000, v3
	v_cmp_gt_f32_e64 s[4:5], s1, v3
	v_cmp_gt_f32_e32 vcc, s1, v2
	s_nop 0
	v_cndmask_b32_e64 v3, v3, v4, s[4:5]
	v_rsq_f32_e32 v3, v3
	s_nop 0
	v_mul_f32_e32 v4, 0x45800000, v3
	v_cndmask_b32_e64 v128, v3, v4, s[4:5]
	v_mul_f32_e32 v3, 0x4b800000, v2
	v_cndmask_b32_e32 v2, v2, v3, vcc
	v_rsq_f32_e32 v2, v2
	s_nop 0
	v_mul_f32_e32 v3, 0x45800000, v2
	v_cndmask_b32_e32 v126, v2, v3, vcc
	v_lshlrev_b64 v[2:3], 6, v[106:107]
	v_lshl_add_u64 v[14:15], s[14:15], 0, v[2:3]
	global_load_dwordx4 v[2:5], v[14:15], off offset:32
	global_load_dwordx4 v[6:9], v[14:15], off offset:16
	global_load_dwordx4 v[10:13], v[14:15], off
	s_nop 0
	global_load_dwordx4 v[14:17], v[14:15], off offset:48
	s_waitcnt vmcnt(2)
	v_mov_b32_e32 v20, v7
	s_waitcnt vmcnt(1)
	v_mov_b32_e32 v18, v11
	v_mov_b32_e32 v19, v12
	v_mov_b32_e32 v21, v8
	v_mov_b32_e32 v11, v13
	v_mov_b32_e32 v7, v9
	v_mov_b32_e32 v8, v3
	v_pk_add_f32 v[10:11], v[18:19], v[10:11]
	v_pk_add_f32 v[6:7], v[20:21], v[6:7]
	v_pk_add_f32 v[2:3], v[2:3], v[8:9]
	v_mov_b32_e32 v8, v5
	v_pk_add_f32 v[10:11], v[10:11], v[10:11] op_sel:[0,1] op_sel_hi:[1,0]
	v_pk_add_f32 v[6:7], v[6:7], v[6:7] op_sel:[0,1] op_sel_hi:[1,0]
	v_pk_add_f32 v[4:5], v[4:5], v[8:9]
	s_waitcnt vmcnt(0)
	v_mov_b32_e32 v11, v14
	v_mov_b32_e32 v7, v15
	v_mov_b32_e32 v3, v16
	v_mov_b32_e32 v5, v17
	v_pk_add_f32 v[6:7], v[10:11], v[6:7]
	v_pk_add_f32 v[2:3], v[2:3], v[4:5]
	s_nop 0
	v_pk_add_f32 v[18:19], v[6:7], v[2:3]
	v_lshlrev_b64 v[2:3], 6, v[104:105]
	v_lshl_add_u64 v[14:15], s[14:15], 0, v[2:3]
	global_load_dwordx4 v[2:5], v[14:15], off offset:32
	global_load_dwordx4 v[6:9], v[14:15], off offset:16
	global_load_dwordx4 v[10:13], v[14:15], off
	s_nop 0
	global_load_dwordx4 v[14:17], v[14:15], off offset:48
	s_waitcnt vmcnt(2)
	v_mov_b32_e32 v22, v7
	s_waitcnt vmcnt(1)
	v_mov_b32_e32 v20, v11
	v_mov_b32_e32 v21, v12
	v_mov_b32_e32 v23, v8
	v_mov_b32_e32 v11, v13
	v_mov_b32_e32 v7, v9
	v_mov_b32_e32 v8, v3
	v_pk_add_f32 v[10:11], v[20:21], v[10:11]
	v_pk_add_f32 v[6:7], v[22:23], v[6:7]
	v_pk_add_f32 v[2:3], v[2:3], v[8:9]
	v_mov_b32_e32 v8, v5
	v_pk_add_f32 v[10:11], v[10:11], v[10:11] op_sel:[0,1] op_sel_hi:[1,0]
	v_pk_add_f32 v[6:7], v[6:7], v[6:7] op_sel:[0,1] op_sel_hi:[1,0]
	v_pk_add_f32 v[4:5], v[4:5], v[8:9]
	s_waitcnt vmcnt(0)
; DI int TIDX() { int t = threadIdx.x; asm volatile("" : "+v"(t)); return t; }
; #define GL_LOAD(s_, kt_) if (VAR != 1) { a##s_##0 = GL_A(0, kt_); a##s_##1 = GL_A(1, kt_); a##s_##2 = GL_A(2, kt_); a##s_##3 = GL_A(3, kt_); b##s_##0 = GL_B(0, kt_); b##s_##1 = GL_B(1, kt_); b##s_##2 = GL_B(2, kt_); b##s_##3 = GL_B(3, kt_); }
; #define LDS_STORE(s_, buf_) if (VAR != 2) { LDS_ST1(sA, 0, buf_, a##s_##0) LDS_ST1(sA, 1, buf_, a##s_##1) LDS_ST1(sA, 2, buf_, a##s_##2) LDS_ST1(sA, 3, buf_, a##s_##3) LDS_ST1(sB, 0, buf_, b##s_##0) LDS_ST1(sB, 1, buf_, b##s_##1) LDS_ST1(sB, 2, buf_, b##s_##2) LDS_ST1(sB, 3, buf_, b##s_##3) }
;   const int tid = TIDX(), lane = tid & 63, wid = tid >> 6, wm = wid >> 1, wn = wid & 1, lr = lane & 15, g = lane >> 4;
;   char* sA = smem; char* sB = smem + 2 * LTILE;
;   uint4 a00 = {}, a01 = {}, a02 = {}, a03 = {}, b00 = {}, b01 = {}, b02 = {}, b03 = {}, a10 = {}, a11 = {}, a12 = {}, a13 = {}, b10 = {}, b11 = {}, b12 = {}, b13 = {};
;   constexpr int nk = NK;
;   const int sw0 = (g ^ ((lr >> 1) & 7)) << 4, sw1 = sw0 ^ 64;
;   const int r0 = tid >> 3, kc = tid & 7, kcs = kc ^ ((r0 >> 1) & 7);
;     ...
;   GL_LOAD(0, 0)
;   GL_LOAD(1, 1)
;   LDS_STORE(0, 0)
;   if (VAR != 4) __syncthreads();
	v_mov_b32_e32 v11, v14
	v_mov_b32_e32 v7, v15
	v_mov_b32_e32 v3, v16
	v_mov_b32_e32 v5, v17
	v_pk_add_f32 v[6:7], v[10:11], v[6:7]
	v_pk_add_f32 v[2:3], v[2:3], v[4:5]
	v_mov_b32_e32 v5, v18
	v_pk_add_f32 v[2:3], v[6:7], v[2:3]
	v_ashrrev_i32_e32 v64, 3, v72
	v_mov_b32_e32 v4, v2
	v_mov_b32_e32 v18, v3
	v_pk_add_f32 v[2:3], v[4:5], v[18:19]
	v_ashrrev_i32_e32 v65, 31, v64
	v_pk_fma_f32 v[0:1], v[2:3], s[16:17], v[0:1] op_sel_hi:[1,0,0]
	v_and_b32_e32 v75, 48, v72
	v_mul_f32_e32 v2, 0x4b800000, v1
	v_cmp_gt_f32_e64 s[4:5], s1, v1
	v_cmp_gt_f32_e32 vcc, s1, v0
	v_lshlrev_b64 v[16:17], 11, v[64:65]
	v_cndmask_b32_e64 v1, v1, v2, s[4:5]
	v_rsq_f32_e32 v1, v1
	v_lshlrev_b32_e32 v65, 4, v72
	v_and_b32_e32 v150, 0x70, v65
	v_add_u32_e32 v66, 32, v64
	v_mul_f32_e32 v2, 0x45800000, v1
	v_cndmask_b32_e64 v129, v1, v2, s[4:5]
	v_mul_f32_e32 v1, 0x4b800000, v0
	v_cndmask_b32_e32 v0, v0, v1, vcc
	v_rsq_f32_e32 v0, v0
	s_lshl_b64 s[4:5], s[8:9], 11
	v_readlane_b32 s8, v254, 43
	v_readlane_b32 s9, v254, 44
	v_mul_f32_e32 v1, 0x45800000, v0
	s_add_u32 s4, s8, s4
	v_cndmask_b32_e32 v127, v0, v1, vcc
	s_addc_u32 s5, s9, s5
	v_lshlrev_b32_e32 v0, 3, v72
	s_ashr_i32 s7, s6, 31
	v_and_b32_e32 v74, 0x70, v0
	v_bitop3_b32 v134, v0, v75, s23 bitop3:0x6c
	v_lshl_add_u64 v[0:1], s[4:5], 0, v[16:17]
	v_add_u32_e32 v68, 64, v64
	v_add_u32_e32 v70, 0x60, v64
	s_lshl_b64 s[6:7], s[6:7], 11
	v_lshl_add_u64 v[108:109], v[0:1], 0, v[150:151]
	v_ashrrev_i32_e32 v67, 31, v66
	v_ashrrev_i32_e32 v69, 31, v68
	v_ashrrev_i32_e32 v71, 31, v70
	s_add_u32 s6, s10, s6
	v_lshlrev_b64 v[20:21], 11, v[66:67]
	v_lshlrev_b64 v[24:25], 11, v[68:69]
	v_lshlrev_b64 v[28:29], 11, v[70:71]
	s_addc_u32 s7, s11, s7
	v_lshl_add_u64 v[4:5], s[4:5], 0, v[20:21]
	v_lshl_add_u64 v[8:9], s[4:5], 0, v[24:25]
	v_lshl_add_u64 v[12:13], s[4:5], 0, v[28:29]
	v_lshl_add_u64 v[110:111], v[4:5], 0, v[150:151]
	v_lshl_add_u64 v[112:113], v[8:9], 0, v[150:151]
	v_lshl_add_u64 v[114:115], v[12:13], 0, v[150:151]
	v_lshl_add_u64 v[16:17], s[6:7], 0, v[16:17]
	v_lshl_add_u64 v[116:117], v[16:17], 0, v[150:151]
	v_lshl_add_u64 v[20:21], s[6:7], 0, v[20:21]
	v_lshl_add_u64 v[118:119], v[20:21], 0, v[150:151]
	v_lshl_add_u64 v[24:25], s[6:7], 0, v[24:25]
	v_lshl_add_u64 v[120:121], v[24:25], 0, v[150:151]
	v_lshl_add_u64 v[28:29], s[6:7], 0, v[28:29]
	v_lshl_add_u64 v[122:123], v[28:29], 0, v[150:151]
	v_bitop3_b32 v65, v65, s23, v72 bitop3:0x48
	v_lshl_or_b32 v101, v64, 7, v65
	v_and_b32_e32 v73, 15, v72
	v_lshl_or_b32 v131, v66, 7, v65
	v_lshl_or_b32 v132, v68, 7, v65
	v_lshl_or_b32 v130, v70, 7, v65
	v_xor_b32_e32 v135, 64, v134
	v_writelane_b32 v255, s60, 0
	v_writelane_b32 v255, s61, 1
	v_writelane_b32 v255, s62, 2
	v_writelane_b32 v255, s63, 3
	v_writelane_b32 v255, s64, 4
	v_writelane_b32 v255, s65, 5
	v_writelane_b32 v255, s66, 6
	v_writelane_b32 v255, s67, 7
	v_writelane_b32 v255, s68, 8
	v_writelane_b32 v255, s69, 9
	v_writelane_b32 v255, s70, 10
	v_writelane_b32 v255, s71, 11
	v_writelane_b32 v255, s72, 12
	v_writelane_b32 v255, s73, 13
	v_writelane_b32 v255, s74, 14
	v_writelane_b32 v255, s75, 15
	v_mov_b32_e32 v3, v101
	v_and_b32_e32 v3, 0xffffff80, v3
	s_nop 0
	v_readfirstlane_b32 s60, v3
	v_add_u32_e32 v3, 0x4000, v101
	v_and_b32_e32 v3, 0xffffff80, v3
	s_nop 0
	v_readfirstlane_b32 s61, v3
	v_add_u32_e32 v3, 0x8000, v101
	v_and_b32_e32 v3, 0xffffff80, v3
	s_nop 0
	v_readfirstlane_b32 s62, v3
	v_add_u32_e32 v3, 0xc000, v101
	v_and_b32_e32 v3, 0xffffff80, v3
	s_nop 0
	v_readfirstlane_b32 s63, v3
	v_mov_b32_e32 v3, v130
	v_and_b32_e32 v3, 0xffffff80, v3
	s_nop 0
	v_readfirstlane_b32 s64, v3
	v_add_u32_e32 v3, 0x4000, v130
	v_and_b32_e32 v3, 0xffffff80, v3
	s_nop 0
	v_readfirstlane_b32 s65, v3
	v_add_u32_e32 v3, 0x8000, v130
	v_and_b32_e32 v3, 0xffffff80, v3
	s_nop 0
	v_readfirstlane_b32 s66, v3
	v_add_u32_e32 v3, 0xc000, v130
	v_and_b32_e32 v3, 0xffffff80, v3
	s_nop 0
	v_readfirstlane_b32 s67, v3
	v_mov_b32_e32 v3, v131
	v_and_b32_e32 v3, 0xffffff80, v3
	s_nop 0
	v_readfirstlane_b32 s68, v3
	v_add_u32_e32 v3, 0x4000, v131
	v_and_b32_e32 v3, 0xffffff80, v3
	s_nop 0
	v_readfirstlane_b32 s69, v3
	v_add_u32_e32 v3, 0x8000, v131
	v_and_b32_e32 v3, 0xffffff80, v3
	s_nop 0
	v_readfirstlane_b32 s70, v3
	v_add_u32_e32 v3, 0xc000, v131
	v_and_b32_e32 v3, 0xffffff80, v3
	s_nop 0
	v_readfirstlane_b32 s71, v3
	v_mov_b32_e32 v3, v132
	v_and_b32_e32 v3, 0xffffff80, v3
	s_nop 0
	v_readfirstlane_b32 s72, v3
	v_add_u32_e32 v3, 0x4000, v132
	v_and_b32_e32 v3, 0xffffff80, v3
	s_nop 0
	v_readfirstlane_b32 s73, v3
	v_add_u32_e32 v3, 0x8000, v132
	v_and_b32_e32 v3, 0xffffff80, v3
	s_nop 0
	v_readfirstlane_b32 s74, v3
	v_add_u32_e32 v3, 0xc000, v132
	v_and_b32_e32 v3, 0xffffff80, v3
	s_nop 0
	v_readfirstlane_b32 s75, v3
	v_and_b32_e32 v30, 7, v148
	v_bfe_u32 v31, v148, 4, 3
	v_xor_b32_e32 v31, v31, v30
	v_sub_u32_e32 v31, v31, v30
	v_lshlrev_b32_e32 v30, 4, v31
	v_ashrrev_i32_e32 v31, 31, v30
	v_lshl_add_u64 v[0:1], v[108:109], 0, v[30:31]
	s_mov_b32 m0, s60
	s_nop 0
	global_load_lds_dwordx4 v[0:1], off
	v_lshrrev_b32_e32 v0, 1, v72
	v_and_or_b32 v0, v0, s24, v73
	v_lshlrev_b32_e32 v137, 7, v0
	v_lshlrev_b32_e32 v0, 7, v72
	v_and_b32_e32 v146, 0x2780, v0
	v_bitop3_b32 v133, v137, v74, v75 bitop3:0xf6
	v_or_b32_e32 v136, v146, v134
	v_bitop3_b32 v134, v137, v134, 64 bitop3:0xf6
	v_or_b32_e32 v135, v146, v135
	v_lshl_add_u64 v[4:5], v[110:111], 0, v[30:31]
	s_mov_b32 m0, s68
	s_nop 0
	global_load_lds_dwordx4 v[4:5], off
	v_lshl_add_u64 v[8:9], v[112:113], 0, v[30:31]
	s_mov_b32 m0, s72
	s_nop 0
	global_load_lds_dwordx4 v[8:9], off
	v_lshl_add_u64 v[12:13], v[114:115], 0, v[30:31]
	s_mov_b32 m0, s64
	s_nop 0
	global_load_lds_dwordx4 v[12:13], off
	v_lshl_add_u64 v[16:17], v[116:117], 0, v[30:31]
	s_mov_b32 m0, s62
	s_nop 0
	global_load_lds_dwordx4 v[16:17], off
	v_lshl_add_u64 v[20:21], v[118:119], 0, v[30:31]
	s_mov_b32 m0, s70
	s_nop 0
	global_load_lds_dwordx4 v[20:21], off
	v_lshl_add_u64 v[24:25], v[120:121], 0, v[30:31]
	s_mov_b32 m0, s74
	s_nop 0
	global_load_lds_dwordx4 v[24:25], off
	v_lshl_add_u64 v[28:29], v[122:123], 0, v[30:31]
	s_mov_b32 m0, s66
	s_nop 0
	global_load_lds_dwordx4 v[28:29], off
	s_waitcnt lgkmcnt(0)
	s_waitcnt vmcnt(0)
	s_barrier
; #define GL_LOAD(s_, kt_) if (VAR != 1) { a##s_##0 = GL_A(0, kt_); a##s_##1 = GL_A(1, kt_); a##s_##2 = GL_A(2, kt_); a##s_##3 = GL_A(3, kt_); b##s_##0 = GL_B(0, kt_); b##s_##1 = GL_B(1, kt_); b##s_##2 = GL_B(2, kt_); b##s_##3 = GL_B(3, kt_); }
; #define LDS_STORE(s_, buf_) if (VAR != 2) { LDS_ST1(sA, 0, buf_, a##s_##0) LDS_ST1(sA, 1, buf_, a##s_##1) LDS_ST1(sA, 2, buf_, a##s_##2) LDS_ST1(sA, 3, buf_, a##s_##3) LDS_ST1(sB, 0, buf_, b##s_##0) LDS_ST1(sB, 1, buf_, b##s_##1) LDS_ST1(sB, 2, buf_, b##s_##2) LDS_ST1(sB, 3, buf_, b##s_##3) }
;     ...
;   for (int kt = 0; kt < nk; kt += 2) {
;     if (kt + 2 < nk) { GL_LOAD(0, kt + 2) }
;     MMA_TILE(0)
;     LDS_STORE(1, 1)
;     if (VAR != 4) __syncthreads();
;     if (kt + 3 < nk) { GL_LOAD(1, kt + 3) }
;     MMA_TILE(1)
;     if (kt + 2 < nk) { LDS_STORE(0, 0) }
;     if (VAR != 4) __syncthreads();
;   }
	s_setprio 1
	ds_read_b128 v[64:67], v133
	ds_read_b128 v[68:71], v136 offset:32768
	s_waitcnt lgkmcnt(0)
	v_mfma_f32_16x16x32_f16 v[138:141], v[68:71], v[64:67], 0
	ds_read_b128 v[72:75], v133 offset:2048
	ds_read_b128 v[76:79], v136 offset:34816
	s_waitcnt lgkmcnt(1)
	v_mfma_f32_16x16x32_f16 v[158:161], v[68:71], v[72:75], 0
	ds_read_b128 v[80:83], v133 offset:4096
	ds_read_b128 v[84:87], v136 offset:36864
	s_waitcnt lgkmcnt(2)
	v_mfma_f32_16x16x32_f16 v[142:145], v[76:79], v[64:67], 0
	ds_read_b128 v[88:91], v133 offset:6144
	ds_read_b128 v[92:95], v136 offset:38912
	v_mfma_f32_16x16x32_f16 v[162:165], v[76:79], v[72:75], 0
	ds_read_b128 v[202:205], v135 offset:32768
	ds_read_b128 v[206:209], v134 offset:2048
	s_waitcnt lgkmcnt(5)
	v_mfma_f32_16x16x32_f16 v[190:193], v[68:71], v[80:83], 0
	ds_read_b128 v[210:213], v135 offset:34816
	ds_read_b128 v[220:223], v134 offset:4096
	s_waitcnt lgkmcnt(5)
	v_mfma_f32_16x16x32_f16 v[68:71], v[68:71], v[88:91], 0
	ds_read_b128 v[224:227], v135 offset:36864
	v_mfma_f32_16x16x32_f16 v[194:197], v[76:79], v[80:83], 0
	ds_read_b128 v[228:231], v134 offset:6144
	v_mfma_f32_16x16x32_f16 v[76:79], v[76:79], v[88:91], 0
	ds_read_b128 v[232:235], v135 offset:38912
	v_mfma_f32_16x16x32_f16 v[154:157], v[84:87], v[64:67], 0
	v_mfma_f32_16x16x32_f16 v[166:169], v[84:87], v[72:75], 0
	s_waitcnt lgkmcnt(7)
	v_mfma_f32_16x16x32_f16 v[64:67], v[92:95], v[64:67], 0
	v_mfma_f32_16x16x32_f16 v[72:75], v[92:95], v[72:75], 0
	v_mfma_f32_16x16x32_f16 v[198:201], v[84:87], v[80:83], 0
	v_and_b32_e32 v62, 7, v148
	v_bfe_u32 v63, v148, 4, 3
	v_xor_b32_e32 v63, v63, v62
	v_sub_u32_e32 v63, v63, v62
	v_lshlrev_b32_e32 v62, 4, v63
	v_add_u32_e32 v62, 0x80, v62
	v_ashrrev_i32_e32 v63, 31, v62
	v_mfma_f32_16x16x32_f16 v[84:87], v[84:87], v[88:91], 0
	v_lshl_add_u64 v[32:33], v[108:109], 0, v[62:63]
	s_mov_b32 m0, s61
	s_nop 0
	global_load_lds_dwordx4 v[32:33], off
	v_lshl_add_u64 v[36:37], v[110:111], 0, v[62:63]
	s_mov_b32 m0, s69
	s_nop 0
	global_load_lds_dwordx4 v[36:37], off
	v_mfma_f32_16x16x32_f16 v[80:83], v[92:95], v[80:83], 0
	v_lshl_add_u64 v[40:41], v[112:113], 0, v[62:63]
	s_mov_b32 m0, s73
	s_nop 0
	global_load_lds_dwordx4 v[40:41], off
	v_lshl_add_u64 v[44:45], v[114:115], 0, v[62:63]
	s_mov_b32 m0, s65
	s_nop 0
	global_load_lds_dwordx4 v[44:45], off
	v_mfma_f32_16x16x32_f16 v[88:91], v[92:95], v[88:91], 0
	ds_read_b128 v[92:95], v134
	v_lshl_add_u64 v[48:49], v[116:117], 0, v[62:63]
	s_mov_b32 m0, s63
	s_nop 0
	global_load_lds_dwordx4 v[48:49], off
	v_lshl_add_u64 v[52:53], v[118:119], 0, v[62:63]
	s_mov_b32 m0, s71
	s_nop 0
	global_load_lds_dwordx4 v[52:53], off
	v_lshl_add_u64 v[56:57], v[120:121], 0, v[62:63]
	s_mov_b32 m0, s75
	s_nop 0
	global_load_lds_dwordx4 v[56:57], off
	v_lshl_add_u64 v[60:61], v[122:123], 0, v[62:63]
	s_mov_b32 m0, s67
	s_nop 0
	global_load_lds_dwordx4 v[60:61], off
	s_waitcnt vmcnt(0) lgkmcnt(0)
	s_barrier
	v_mfma_f32_16x16x32_f16 v[138:141], v[202:205], v[92:95], v[138:141]
	v_mfma_f32_16x16x32_f16 v[142:145], v[210:213], v[92:95], v[142:145]
	v_mfma_f32_16x16x32_f16 v[154:157], v[224:227], v[92:95], v[154:157]
	v_mfma_f32_16x16x32_f16 v[64:67], v[232:235], v[92:95], v[64:67]
	v_mfma_f32_16x16x32_f16 v[92:95], v[202:205], v[206:209], v[158:161]
	v_mfma_f32_16x16x32_f16 v[158:161], v[210:213], v[206:209], v[162:165]
	v_mfma_f32_16x16x32_f16 v[162:165], v[224:227], v[206:209], v[166:169]
	v_mfma_f32_16x16x32_f16 v[166:169], v[202:205], v[220:223], v[190:193]
	v_mfma_f32_16x16x32_f16 v[68:71], v[202:205], v[228:231], v[68:71]
	ds_read_b128 v[202:205], v136 offset:49152
	v_mfma_f32_16x16x32_f16 v[190:193], v[210:213], v[220:223], v[194:197]
	v_mfma_f32_16x16x32_f16 v[76:79], v[210:213], v[228:231], v[76:79]
	ds_read_b128 v[210:213], v136 offset:51200
	v_and_b32_e32 v30, 7, v148
	v_bfe_u32 v31, v148, 4, 3
	v_xor_b32_e32 v31, v31, v30
	v_sub_u32_e32 v31, v31, v30
	v_lshlrev_b32_e32 v30, 4, v31
	v_add_u32_e32 v30, 0x100, v30
	v_ashrrev_i32_e32 v31, 31, v30
	v_mfma_f32_16x16x32_f16 v[72:75], v[232:235], v[206:209], v[72:75]
	ds_read_b128 v[206:209], v133 offset:18432
	v_mfma_f32_16x16x32_f16 v[194:197], v[224:227], v[220:223], v[198:201]
	s_nop 2
	ds_read_b128 v[198:201], v133 offset:16384
	v_mfma_f32_16x16x32_f16 v[84:87], v[224:227], v[228:231], v[84:87]
	ds_read_b128 v[224:227], v136 offset:53248
	v_mfma_f32_16x16x32_f16 v[80:83], v[232:235], v[220:223], v[80:83]
	ds_read_b128 v[220:223], v133 offset:20480
	v_mfma_f32_16x16x32_f16 v[88:91], v[232:235], v[228:231], v[88:91]
	ds_read_b128 v[228:231], v133 offset:22528
	s_waitcnt lgkmcnt(3)
	v_mfma_f32_16x16x32_f16 v[138:141], v[202:205], v[198:201], v[138:141]
	ds_read_b128 v[232:235], v136 offset:55296
	v_mfma_f32_16x16x32_f16 v[92:95], v[202:205], v[206:209], v[92:95]
	v_lshl_add_u64 v[0:1], v[108:109], 0, v[30:31]
	s_mov_b32 m0, s60
	s_nop 0
	global_load_lds_dwordx4 v[0:1], off
	v_mfma_f32_16x16x32_f16 v[142:145], v[210:213], v[198:201], v[142:145]
	v_lshl_add_u64 v[4:5], v[110:111], 0, v[30:31]
	s_mov_b32 m0, s68
	s_nop 0
	global_load_lds_dwordx4 v[4:5], off
	v_mfma_f32_16x16x32_f16 v[158:161], v[210:213], v[206:209], v[158:161]
	v_lshl_add_u64 v[8:9], v[112:113], 0, v[30:31]
	s_mov_b32 m0, s72
	s_nop 0
	global_load_lds_dwordx4 v[8:9], off
	s_waitcnt lgkmcnt(2)
	v_mfma_f32_16x16x32_f16 v[166:169], v[202:205], v[220:223], v[166:169]
	v_lshl_add_u64 v[12:13], v[114:115], 0, v[30:31]
	s_mov_b32 m0, s64
	s_nop 0
	global_load_lds_dwordx4 v[12:13], off
	s_waitcnt lgkmcnt(1)
; #define GL_LOAD(s_, kt_) if (VAR != 1) { a##s_##0 = GL_A(0, kt_); a##s_##1 = GL_A(1, kt_); a##s_##2 = GL_A(2, kt_); a##s_##3 = GL_A(3, kt_); b##s_##0 = GL_B(0, kt_); b##s_##1 = GL_B(1, kt_); b##s_##2 = GL_B(2, kt_); b##s_##3 = GL_B(3, kt_); }
; #define LDS_STORE(s_, buf_) if (VAR != 2) { LDS_ST1(sA, 0, buf_, a##s_##0) LDS_ST1(sA, 1, buf_, a##s_##1) LDS_ST1(sA, 2, buf_, a##s_##2) LDS_ST1(sA, 3, buf_, a##s_##3) LDS_ST1(sB, 0, buf_, b##s_##0) LDS_ST1(sB, 1, buf_, b##s_##1) LDS_ST1(sB, 2, buf_, b##s_##2) LDS_ST1(sB, 3, buf_, b##s_##3) }
;     ...
;   for (int kt = 0; kt < nk; kt += 2) {
;     if (kt + 2 < nk) { GL_LOAD(0, kt + 2) }
;     MMA_TILE(0)
;     LDS_STORE(1, 1)
;     if (VAR != 4) __syncthreads();
;     if (kt + 3 < nk) { GL_LOAD(1, kt + 3) }
;     MMA_TILE(1)
;     if (kt + 2 < nk) { LDS_STORE(0, 0) }
;     if (VAR != 4) __syncthreads();
;   }
	v_mfma_f32_16x16x32_f16 v[68:71], v[202:205], v[228:231], v[68:71]
	ds_read_b128 v[202:205], v135 offset:49152
	v_mfma_f32_16x16x32_f16 v[190:193], v[210:213], v[220:223], v[190:193]
	v_lshl_add_u64 v[16:17], v[116:117], 0, v[30:31]
	s_mov_b32 m0, s62
	s_nop 0
	global_load_lds_dwordx4 v[16:17], off
	v_mfma_f32_16x16x32_f16 v[76:79], v[210:213], v[228:231], v[76:79]
	ds_read_b128 v[210:213], v135 offset:51200
	v_mfma_f32_16x16x32_f16 v[154:157], v[224:227], v[198:201], v[154:157]
	v_lshl_add_u64 v[20:21], v[118:119], 0, v[30:31]
	s_mov_b32 m0, s70
	s_nop 0
	global_load_lds_dwordx4 v[20:21], off
	v_mfma_f32_16x16x32_f16 v[162:165], v[224:227], v[206:209], v[162:165]
	v_lshl_add_u64 v[24:25], v[120:121], 0, v[30:31]
	s_mov_b32 m0, s74
	s_nop 0
	global_load_lds_dwordx4 v[24:25], off
	s_waitcnt lgkmcnt(2)
	v_mfma_f32_16x16x32_f16 v[64:67], v[232:235], v[198:201], v[64:67]
	ds_read_b128 v[198:201], v134 offset:16384
	v_mfma_f32_16x16x32_f16 v[72:75], v[232:235], v[206:209], v[72:75]
	ds_read_b128 v[206:209], v134 offset:18432
	v_mfma_f32_16x16x32_f16 v[194:197], v[224:227], v[220:223], v[194:197]
	v_lshl_add_u64 v[28:29], v[122:123], 0, v[30:31]
	s_mov_b32 m0, s66
	s_nop 0
	global_load_lds_dwordx4 v[28:29], off
	v_mfma_f32_16x16x32_f16 v[84:87], v[224:227], v[228:231], v[84:87]
	ds_read_b128 v[224:227], v135 offset:53248
	v_mfma_f32_16x16x32_f16 v[80:83], v[232:235], v[220:223], v[80:83]
	ds_read_b128 v[220:223], v134 offset:20480
	v_mfma_f32_16x16x32_f16 v[88:91], v[232:235], v[228:231], v[88:91]
	ds_read_b128 v[228:231], v134 offset:22528
	ds_read_b128 v[232:235], v135 offset:55296
	s_waitcnt vmcnt(0) lgkmcnt(0)
	s_barrier
	v_mfma_f32_16x16x32_f16 v[138:141], v[202:205], v[198:201], v[138:141]
	v_mfma_f32_16x16x32_f16 v[92:95], v[202:205], v[206:209], v[92:95]
	v_mfma_f32_16x16x32_f16 v[142:145], v[210:213], v[198:201], v[142:145]
	v_mfma_f32_16x16x32_f16 v[158:161], v[210:213], v[206:209], v[158:161]
	v_mfma_f32_16x16x32_f16 v[166:169], v[202:205], v[220:223], v[166:169]
	v_mfma_f32_16x16x32_f16 v[68:71], v[202:205], v[228:231], v[68:71]
	ds_read_b128 v[202:205], v136 offset:32768
	v_mfma_f32_16x16x32_f16 v[190:193], v[210:213], v[220:223], v[190:193]
	v_mfma_f32_16x16x32_f16 v[76:79], v[210:213], v[228:231], v[76:79]
	ds_read_b128 v[210:213], v136 offset:34816
	v_mfma_f32_16x16x32_f16 v[154:157], v[224:227], v[198:201], v[154:157]
	v_mfma_f32_16x16x32_f16 v[162:165], v[224:227], v[206:209], v[162:165]
	v_mfma_f32_16x16x32_f16 v[64:67], v[232:235], v[198:201], v[64:67]
	ds_read_b128 v[198:201], v133
	v_mfma_f32_16x16x32_f16 v[72:75], v[232:235], v[206:209], v[72:75]
	ds_read_b128 v[206:209], v133 offset:2048
	v_mfma_f32_16x16x32_f16 v[194:197], v[224:227], v[220:223], v[194:197]
	v_and_b32_e32 v62, 7, v148
	v_bfe_u32 v63, v148, 4, 3
	v_xor_b32_e32 v63, v63, v62
	v_sub_u32_e32 v63, v63, v62
	v_lshlrev_b32_e32 v62, 4, v63
	v_add_u32_e32 v62, 0x180, v62
	v_ashrrev_i32_e32 v63, 31, v62
	v_mfma_f32_16x16x32_f16 v[84:87], v[224:227], v[228:231], v[84:87]
	ds_read_b128 v[224:227], v136 offset:36864
	v_mfma_f32_16x16x32_f16 v[80:83], v[232:235], v[220:223], v[80:83]
	ds_read_b128 v[220:223], v133 offset:4096
	v_mfma_f32_16x16x32_f16 v[88:91], v[232:235], v[228:231], v[88:91]
	ds_read_b128 v[228:231], v133 offset:6144
	s_waitcnt lgkmcnt(4)
	v_mfma_f32_16x16x32_f16 v[138:141], v[202:205], v[198:201], v[138:141]
	ds_read_b128 v[232:235], v136 offset:38912
	s_waitcnt lgkmcnt(4)
	v_mfma_f32_16x16x32_f16 v[92:95], v[202:205], v[206:209], v[92:95]
	v_lshl_add_u64 v[32:33], v[108:109], 0, v[62:63]
	s_mov_b32 m0, s61
	s_nop 0
	global_load_lds_dwordx4 v[32:33], off
	v_mfma_f32_16x16x32_f16 v[142:145], v[210:213], v[198:201], v[142:145]
	v_lshl_add_u64 v[36:37], v[110:111], 0, v[62:63]
	s_mov_b32 m0, s69
	s_nop 0
	global_load_lds_dwordx4 v[36:37], off
	v_mfma_f32_16x16x32_f16 v[158:161], v[210:213], v[206:209], v[158:161]
	v_lshl_add_u64 v[40:41], v[112:113], 0, v[62:63]
	s_mov_b32 m0, s73
	s_nop 0
	global_load_lds_dwordx4 v[40:41], off
	s_waitcnt lgkmcnt(2)
	v_mfma_f32_16x16x32_f16 v[166:169], v[202:205], v[220:223], v[166:169]
	v_lshl_add_u64 v[44:45], v[114:115], 0, v[62:63]
	s_mov_b32 m0, s65
	s_nop 0
	global_load_lds_dwordx4 v[44:45], off
	s_waitcnt lgkmcnt(1)
	v_mfma_f32_16x16x32_f16 v[68:71], v[202:205], v[228:231], v[68:71]
	ds_read_b128 v[202:205], v135 offset:32768
	v_mfma_f32_16x16x32_f16 v[190:193], v[210:213], v[220:223], v[190:193]
	v_lshl_add_u64 v[48:49], v[116:117], 0, v[62:63]
	s_mov_b32 m0, s63
	s_nop 0
	global_load_lds_dwordx4 v[48:49], off
	v_mfma_f32_16x16x32_f16 v[76:79], v[210:213], v[228:231], v[76:79]
	ds_read_b128 v[210:213], v135 offset:34816
	v_mfma_f32_16x16x32_f16 v[154:157], v[224:227], v[198:201], v[154:157]
	v_lshl_add_u64 v[52:53], v[118:119], 0, v[62:63]
	s_mov_b32 m0, s71
	s_nop 0
	global_load_lds_dwordx4 v[52:53], off
	v_mfma_f32_16x16x32_f16 v[162:165], v[224:227], v[206:209], v[162:165]
	v_lshl_add_u64 v[56:57], v[120:121], 0, v[62:63]
	s_mov_b32 m0, s75
	s_nop 0
	global_load_lds_dwordx4 v[56:57], off
	s_waitcnt lgkmcnt(2)
	v_mfma_f32_16x16x32_f16 v[64:67], v[232:235], v[198:201], v[64:67]
	ds_read_b128 v[198:201], v134
	v_mfma_f32_16x16x32_f16 v[72:75], v[232:235], v[206:209], v[72:75]
	ds_read_b128 v[206:209], v134 offset:2048
	v_mfma_f32_16x16x32_f16 v[194:197], v[224:227], v[220:223], v[194:197]
	v_lshl_add_u64 v[60:61], v[122:123], 0, v[62:63]
	s_mov_b32 m0, s67
	s_nop 0
	global_load_lds_dwordx4 v[60:61], off
	v_mfma_f32_16x16x32_f16 v[84:87], v[224:227], v[228:231], v[84:87]
	ds_read_b128 v[224:227], v135 offset:36864
	v_mfma_f32_16x16x32_f16 v[80:83], v[232:235], v[220:223], v[80:83]
	ds_read_b128 v[220:223], v134 offset:4096
	v_mfma_f32_16x16x32_f16 v[88:91], v[232:235], v[228:231], v[88:91]
	ds_read_b128 v[228:231], v134 offset:6144
	ds_read_b128 v[232:235], v135 offset:38912
	s_waitcnt vmcnt(0) lgkmcnt(0)
	s_barrier
; #define GL_LOAD(s_, kt_) if (VAR != 1) { a##s_##0 = GL_A(0, kt_); a##s_##1 = GL_A(1, kt_); a##s_##2 = GL_A(2, kt_); a##s_##3 = GL_A(3, kt_); b##s_##0 = GL_B(0, kt_); b##s_##1 = GL_B(1, kt_); b##s_##2 = GL_B(2, kt_); b##s_##3 = GL_B(3, kt_); }
; #define LDS_STORE(s_, buf_) if (VAR != 2) { LDS_ST1(sA, 0, buf_, a##s_##0) LDS_ST1(sA, 1, buf_, a##s_##1) LDS_ST1(sA, 2, buf_, a##s_##2) LDS_ST1(sA, 3, buf_, a##s_##3) LDS_ST1(sB, 0, buf_, b##s_##0) LDS_ST1(sB, 1, buf_, b##s_##1) LDS_ST1(sB, 2, buf_, b##s_##2) LDS_ST1(sB, 3, buf_, b##s_##3) }
;     ...
;   for (int kt = 0; kt < nk; kt += 2) {
;     if (kt + 2 < nk) { GL_LOAD(0, kt + 2) }
;     MMA_TILE(0)
;     LDS_STORE(1, 1)
;     if (VAR != 4) __syncthreads();
;     if (kt + 3 < nk) { GL_LOAD(1, kt + 3) }
;     MMA_TILE(1)
;     if (kt + 2 < nk) { LDS_STORE(0, 0) }
;     if (VAR != 4) __syncthreads();
;   }
	v_mfma_f32_16x16x32_f16 v[138:141], v[202:205], v[198:201], v[138:141]
	v_mfma_f32_16x16x32_f16 v[92:95], v[202:205], v[206:209], v[92:95]
	v_mfma_f32_16x16x32_f16 v[142:145], v[210:213], v[198:201], v[142:145]
	v_mfma_f32_16x16x32_f16 v[158:161], v[210:213], v[206:209], v[158:161]
	v_mfma_f32_16x16x32_f16 v[166:169], v[202:205], v[220:223], v[166:169]
	v_mfma_f32_16x16x32_f16 v[68:71], v[202:205], v[228:231], v[68:71]
	ds_read_b128 v[202:205], v136 offset:49152
	v_mfma_f32_16x16x32_f16 v[190:193], v[210:213], v[220:223], v[190:193]
	v_mfma_f32_16x16x32_f16 v[76:79], v[210:213], v[228:231], v[76:79]
	ds_read_b128 v[210:213], v136 offset:51200
	v_mfma_f32_16x16x32_f16 v[154:157], v[224:227], v[198:201], v[154:157]
	v_mfma_f32_16x16x32_f16 v[162:165], v[224:227], v[206:209], v[162:165]
	v_mfma_f32_16x16x32_f16 v[64:67], v[232:235], v[198:201], v[64:67]
	ds_read_b128 v[198:201], v133 offset:16384
	v_mfma_f32_16x16x32_f16 v[72:75], v[232:235], v[206:209], v[72:75]
	ds_read_b128 v[206:209], v133 offset:18432
	v_mfma_f32_16x16x32_f16 v[194:197], v[224:227], v[220:223], v[194:197]
	v_and_b32_e32 v30, 7, v148
	v_bfe_u32 v31, v148, 4, 3
	v_xor_b32_e32 v31, v31, v30
	v_sub_u32_e32 v31, v31, v30
	v_lshlrev_b32_e32 v30, 4, v31
	v_add_u32_e32 v30, 0x200, v30
	v_ashrrev_i32_e32 v31, 31, v30
	v_mfma_f32_16x16x32_f16 v[84:87], v[224:227], v[228:231], v[84:87]
	ds_read_b128 v[224:227], v136 offset:53248
	v_mfma_f32_16x16x32_f16 v[80:83], v[232:235], v[220:223], v[80:83]
	ds_read_b128 v[220:223], v133 offset:20480
	v_mfma_f32_16x16x32_f16 v[88:91], v[232:235], v[228:231], v[88:91]
	ds_read_b128 v[228:231], v133 offset:22528
	s_waitcnt lgkmcnt(4)
	v_mfma_f32_16x16x32_f16 v[138:141], v[202:205], v[198:201], v[138:141]
	ds_read_b128 v[232:235], v136 offset:55296
	s_waitcnt lgkmcnt(4)
	v_mfma_f32_16x16x32_f16 v[92:95], v[202:205], v[206:209], v[92:95]
	v_lshl_add_u64 v[0:1], v[108:109], 0, v[30:31]
	s_mov_b32 m0, s60
	s_nop 0
	global_load_lds_dwordx4 v[0:1], off
	v_mfma_f32_16x16x32_f16 v[142:145], v[210:213], v[198:201], v[142:145]
	v_lshl_add_u64 v[4:5], v[110:111], 0, v[30:31]
	s_mov_b32 m0, s68
	s_nop 0
	global_load_lds_dwordx4 v[4:5], off
	v_mfma_f32_16x16x32_f16 v[158:161], v[210:213], v[206:209], v[158:161]
	v_lshl_add_u64 v[8:9], v[112:113], 0, v[30:31]
	s_mov_b32 m0, s72
	s_nop 0
	global_load_lds_dwordx4 v[8:9], off
	s_waitcnt lgkmcnt(2)
	v_mfma_f32_16x16x32_f16 v[166:169], v[202:205], v[220:223], v[166:169]
	v_lshl_add_u64 v[12:13], v[114:115], 0, v[30:31]
	s_mov_b32 m0, s64
	s_nop 0
	global_load_lds_dwordx4 v[12:13], off
	s_waitcnt lgkmcnt(1)
	v_mfma_f32_16x16x32_f16 v[68:71], v[202:205], v[228:231], v[68:71]
	ds_read_b128 v[202:205], v135 offset:49152
	v_mfma_f32_16x16x32_f16 v[190:193], v[210:213], v[220:223], v[190:193]
	v_lshl_add_u64 v[16:17], v[116:117], 0, v[30:31]
	s_mov_b32 m0, s62
	s_nop 0
	global_load_lds_dwordx4 v[16:17], off
	v_mfma_f32_16x16x32_f16 v[76:79], v[210:213], v[228:231], v[76:79]
	ds_read_b128 v[210:213], v135 offset:51200
	v_mfma_f32_16x16x32_f16 v[154:157], v[224:227], v[198:201], v[154:157]
	v_lshl_add_u64 v[20:21], v[118:119], 0, v[30:31]
	s_mov_b32 m0, s70
	s_nop 0
	global_load_lds_dwordx4 v[20:21], off
	v_mfma_f32_16x16x32_f16 v[162:165], v[224:227], v[206:209], v[162:165]
	v_lshl_add_u64 v[24:25], v[120:121], 0, v[30:31]
	s_mov_b32 m0, s74
	s_nop 0
	global_load_lds_dwordx4 v[24:25], off
	s_waitcnt lgkmcnt(2)
	v_mfma_f32_16x16x32_f16 v[64:67], v[232:235], v[198:201], v[64:67]
	ds_read_b128 v[198:201], v134 offset:16384
	v_mfma_f32_16x16x32_f16 v[72:75], v[232:235], v[206:209], v[72:75]
	ds_read_b128 v[206:209], v134 offset:18432
	v_mfma_f32_16x16x32_f16 v[194:197], v[224:227], v[220:223], v[194:197]
	v_lshl_add_u64 v[28:29], v[122:123], 0, v[30:31]
	s_mov_b32 m0, s66
	s_nop 0
	global_load_lds_dwordx4 v[28:29], off
	v_mfma_f32_16x16x32_f16 v[84:87], v[224:227], v[228:231], v[84:87]
	ds_read_b128 v[224:227], v135 offset:53248
	v_mfma_f32_16x16x32_f16 v[80:83], v[232:235], v[220:223], v[80:83]
	ds_read_b128 v[220:223], v134 offset:20480
	v_mfma_f32_16x16x32_f16 v[88:91], v[232:235], v[228:231], v[88:91]
	ds_read_b128 v[228:231], v134 offset:22528
	ds_read_b128 v[232:235], v135 offset:55296
	s_waitcnt vmcnt(0) lgkmcnt(0)
	s_barrier
	v_mfma_f32_16x16x32_f16 v[138:141], v[202:205], v[198:201], v[138:141]
	v_mfma_f32_16x16x32_f16 v[92:95], v[202:205], v[206:209], v[92:95]
	v_mfma_f32_16x16x32_f16 v[142:145], v[210:213], v[198:201], v[142:145]
	v_mfma_f32_16x16x32_f16 v[158:161], v[210:213], v[206:209], v[158:161]
	v_mfma_f32_16x16x32_f16 v[166:169], v[202:205], v[220:223], v[166:169]
	v_mfma_f32_16x16x32_f16 v[68:71], v[202:205], v[228:231], v[68:71]
	ds_read_b128 v[202:205], v136 offset:32768
	v_mfma_f32_16x16x32_f16 v[190:193], v[210:213], v[220:223], v[190:193]
	v_mfma_f32_16x16x32_f16 v[76:79], v[210:213], v[228:231], v[76:79]
	ds_read_b128 v[210:213], v136 offset:34816
	v_mfma_f32_16x16x32_f16 v[154:157], v[224:227], v[198:201], v[154:157]
	v_mfma_f32_16x16x32_f16 v[162:165], v[224:227], v[206:209], v[162:165]
	v_mfma_f32_16x16x32_f16 v[64:67], v[232:235], v[198:201], v[64:67]
	ds_read_b128 v[198:201], v133
	v_mfma_f32_16x16x32_f16 v[72:75], v[232:235], v[206:209], v[72:75]
	ds_read_b128 v[206:209], v133 offset:2048
	v_mfma_f32_16x16x32_f16 v[194:197], v[224:227], v[220:223], v[194:197]
	v_and_b32_e32 v62, 7, v148
	v_bfe_u32 v63, v148, 4, 3
	v_xor_b32_e32 v63, v63, v62
	v_sub_u32_e32 v63, v63, v62
	v_lshlrev_b32_e32 v62, 4, v63
	v_add_u32_e32 v62, 0x280, v62
	v_ashrrev_i32_e32 v63, 31, v62
	v_mfma_f32_16x16x32_f16 v[84:87], v[224:227], v[228:231], v[84:87]
	ds_read_b128 v[224:227], v136 offset:36864
	v_mfma_f32_16x16x32_f16 v[80:83], v[232:235], v[220:223], v[80:83]
	ds_read_b128 v[220:223], v133 offset:4096
	v_mfma_f32_16x16x32_f16 v[88:91], v[232:235], v[228:231], v[88:91]
	ds_read_b128 v[228:231], v133 offset:6144
	s_waitcnt lgkmcnt(4)
; #define GL_LOAD(s_, kt_) if (VAR != 1) { a##s_##0 = GL_A(0, kt_); a##s_##1 = GL_A(1, kt_); a##s_##2 = GL_A(2, kt_); a##s_##3 = GL_A(3, kt_); b##s_##0 = GL_B(0, kt_); b##s_##1 = GL_B(1, kt_); b##s_##2 = GL_B(2, kt_); b##s_##3 = GL_B(3, kt_); }
; #define LDS_STORE(s_, buf_) if (VAR != 2) { LDS_ST1(sA, 0, buf_, a##s_##0) LDS_ST1(sA, 1, buf_, a##s_##1) LDS_ST1(sA, 2, buf_, a##s_##2) LDS_ST1(sA, 3, buf_, a##s_##3) LDS_ST1(sB, 0, buf_, b##s_##0) LDS_ST1(sB, 1, buf_, b##s_##1) LDS_ST1(sB, 2, buf_, b##s_##2) LDS_ST1(sB, 3, buf_, b##s_##3) }
;     ...
;   for (int kt = 0; kt < nk; kt += 2) {
;     if (kt + 2 < nk) { GL_LOAD(0, kt + 2) }
;     MMA_TILE(0)
;     LDS_STORE(1, 1)
;     if (VAR != 4) __syncthreads();
;     if (kt + 3 < nk) { GL_LOAD(1, kt + 3) }
;     MMA_TILE(1)
;     if (kt + 2 < nk) { LDS_STORE(0, 0) }
;     if (VAR != 4) __syncthreads();
;   }
	v_mfma_f32_16x16x32_f16 v[138:141], v[202:205], v[198:201], v[138:141]
	ds_read_b128 v[232:235], v136 offset:38912
	s_waitcnt lgkmcnt(4)
	v_mfma_f32_16x16x32_f16 v[92:95], v[202:205], v[206:209], v[92:95]
	v_lshl_add_u64 v[32:33], v[108:109], 0, v[62:63]
	s_mov_b32 m0, s61
	s_nop 0
	global_load_lds_dwordx4 v[32:33], off
	v_mfma_f32_16x16x32_f16 v[142:145], v[210:213], v[198:201], v[142:145]
	v_lshl_add_u64 v[36:37], v[110:111], 0, v[62:63]
	s_mov_b32 m0, s69
	s_nop 0
	global_load_lds_dwordx4 v[36:37], off
	v_mfma_f32_16x16x32_f16 v[158:161], v[210:213], v[206:209], v[158:161]
	v_lshl_add_u64 v[40:41], v[112:113], 0, v[62:63]
	s_mov_b32 m0, s73
	s_nop 0
	global_load_lds_dwordx4 v[40:41], off
	s_waitcnt lgkmcnt(2)
	v_mfma_f32_16x16x32_f16 v[166:169], v[202:205], v[220:223], v[166:169]
	v_lshl_add_u64 v[44:45], v[114:115], 0, v[62:63]
	s_mov_b32 m0, s65
	s_nop 0
	global_load_lds_dwordx4 v[44:45], off
	s_waitcnt lgkmcnt(1)
	v_mfma_f32_16x16x32_f16 v[68:71], v[202:205], v[228:231], v[68:71]
	ds_read_b128 v[202:205], v135 offset:32768
	v_mfma_f32_16x16x32_f16 v[190:193], v[210:213], v[220:223], v[190:193]
	v_lshl_add_u64 v[48:49], v[116:117], 0, v[62:63]
	s_mov_b32 m0, s63
	s_nop 0
	global_load_lds_dwordx4 v[48:49], off
	v_mfma_f32_16x16x32_f16 v[76:79], v[210:213], v[228:231], v[76:79]
	ds_read_b128 v[210:213], v135 offset:34816
	v_mfma_f32_16x16x32_f16 v[154:157], v[224:227], v[198:201], v[154:157]
	v_lshl_add_u64 v[52:53], v[118:119], 0, v[62:63]
	s_mov_b32 m0, s71
	s_nop 0
	global_load_lds_dwordx4 v[52:53], off
	v_mfma_f32_16x16x32_f16 v[162:165], v[224:227], v[206:209], v[162:165]
	v_lshl_add_u64 v[56:57], v[120:121], 0, v[62:63]
	s_mov_b32 m0, s75
	s_nop 0
	global_load_lds_dwordx4 v[56:57], off
	s_waitcnt lgkmcnt(2)
	v_mfma_f32_16x16x32_f16 v[64:67], v[232:235], v[198:201], v[64:67]
	ds_read_b128 v[198:201], v134
	v_mfma_f32_16x16x32_f16 v[72:75], v[232:235], v[206:209], v[72:75]
	ds_read_b128 v[206:209], v134 offset:2048
	v_mfma_f32_16x16x32_f16 v[194:197], v[224:227], v[220:223], v[194:197]
	v_lshl_add_u64 v[60:61], v[122:123], 0, v[62:63]
	s_mov_b32 m0, s67
	s_nop 0
	global_load_lds_dwordx4 v[60:61], off
	v_mfma_f32_16x16x32_f16 v[84:87], v[224:227], v[228:231], v[84:87]
	ds_read_b128 v[224:227], v135 offset:36864
	v_mfma_f32_16x16x32_f16 v[80:83], v[232:235], v[220:223], v[80:83]
	ds_read_b128 v[220:223], v134 offset:4096
	v_mfma_f32_16x16x32_f16 v[88:91], v[232:235], v[228:231], v[88:91]
	ds_read_b128 v[228:231], v134 offset:6144
	ds_read_b128 v[232:235], v135 offset:38912
	s_waitcnt vmcnt(0) lgkmcnt(0)
	s_barrier
	v_mfma_f32_16x16x32_f16 v[138:141], v[202:205], v[198:201], v[138:141]
	v_mfma_f32_16x16x32_f16 v[92:95], v[202:205], v[206:209], v[92:95]
	v_mfma_f32_16x16x32_f16 v[142:145], v[210:213], v[198:201], v[142:145]
	v_mfma_f32_16x16x32_f16 v[158:161], v[210:213], v[206:209], v[158:161]
	v_mfma_f32_16x16x32_f16 v[166:169], v[202:205], v[220:223], v[166:169]
	v_mfma_f32_16x16x32_f16 v[68:71], v[202:205], v[228:231], v[68:71]
	ds_read_b128 v[202:205], v136 offset:49152
	v_mfma_f32_16x16x32_f16 v[190:193], v[210:213], v[220:223], v[190:193]
	v_mfma_f32_16x16x32_f16 v[76:79], v[210:213], v[228:231], v[76:79]
	ds_read_b128 v[210:213], v136 offset:51200
	v_mfma_f32_16x16x32_f16 v[154:157], v[224:227], v[198:201], v[154:157]
	v_mfma_f32_16x16x32_f16 v[162:165], v[224:227], v[206:209], v[162:165]
	v_mfma_f32_16x16x32_f16 v[64:67], v[232:235], v[198:201], v[64:67]
	ds_read_b128 v[198:201], v133 offset:16384
	v_mfma_f32_16x16x32_f16 v[72:75], v[232:235], v[206:209], v[72:75]
	ds_read_b128 v[206:209], v133 offset:18432
	v_mfma_f32_16x16x32_f16 v[194:197], v[224:227], v[220:223], v[194:197]
	v_and_b32_e32 v30, 7, v148
	v_bfe_u32 v31, v148, 4, 3
	v_xor_b32_e32 v31, v31, v30
	v_sub_u32_e32 v31, v31, v30
	v_lshlrev_b32_e32 v30, 4, v31
	v_add_u32_e32 v30, 0x300, v30
	v_ashrrev_i32_e32 v31, 31, v30
	v_mfma_f32_16x16x32_f16 v[84:87], v[224:227], v[228:231], v[84:87]
	ds_read_b128 v[224:227], v136 offset:53248
	v_mfma_f32_16x16x32_f16 v[80:83], v[232:235], v[220:223], v[80:83]
	ds_read_b128 v[220:223], v133 offset:20480
	v_mfma_f32_16x16x32_f16 v[88:91], v[232:235], v[228:231], v[88:91]
	ds_read_b128 v[228:231], v133 offset:22528
	s_waitcnt lgkmcnt(4)
	v_mfma_f32_16x16x32_f16 v[138:141], v[202:205], v[198:201], v[138:141]
	ds_read_b128 v[232:235], v136 offset:55296
	s_waitcnt lgkmcnt(4)
	v_mfma_f32_16x16x32_f16 v[92:95], v[202:205], v[206:209], v[92:95]
	v_lshl_add_u64 v[0:1], v[108:109], 0, v[30:31]
	s_mov_b32 m0, s60
	s_nop 0
	global_load_lds_dwordx4 v[0:1], off
	v_mfma_f32_16x16x32_f16 v[142:145], v[210:213], v[198:201], v[142:145]
	v_lshl_add_u64 v[4:5], v[110:111], 0, v[30:31]
	s_mov_b32 m0, s68
	s_nop 0
	global_load_lds_dwordx4 v[4:5], off
	v_mfma_f32_16x16x32_f16 v[158:161], v[210:213], v[206:209], v[158:161]
	v_lshl_add_u64 v[8:9], v[112:113], 0, v[30:31]
	s_mov_b32 m0, s72
	s_nop 0
	global_load_lds_dwordx4 v[8:9], off
	s_waitcnt lgkmcnt(2)
	v_mfma_f32_16x16x32_f16 v[166:169], v[202:205], v[220:223], v[166:169]
	v_lshl_add_u64 v[12:13], v[114:115], 0, v[30:31]
	s_mov_b32 m0, s64
	s_nop 0
	global_load_lds_dwordx4 v[12:13], off
	s_waitcnt lgkmcnt(1)
	v_mfma_f32_16x16x32_f16 v[68:71], v[202:205], v[228:231], v[68:71]
	ds_read_b128 v[202:205], v135 offset:49152
	v_mfma_f32_16x16x32_f16 v[190:193], v[210:213], v[220:223], v[190:193]
	v_lshl_add_u64 v[16:17], v[116:117], 0, v[30:31]
	s_mov_b32 m0, s62
	s_nop 0
	global_load_lds_dwordx4 v[16:17], off
	v_mfma_f32_16x16x32_f16 v[76:79], v[210:213], v[228:231], v[76:79]
	ds_read_b128 v[210:213], v135 offset:51200
	v_mfma_f32_16x16x32_f16 v[154:157], v[224:227], v[198:201], v[154:157]
	v_lshl_add_u64 v[20:21], v[118:119], 0, v[30:31]
	s_mov_b32 m0, s70
	s_nop 0
	global_load_lds_dwordx4 v[20:21], off
	v_mfma_f32_16x16x32_f16 v[162:165], v[224:227], v[206:209], v[162:165]
	v_lshl_add_u64 v[24:25], v[120:121], 0, v[30:31]
	s_mov_b32 m0, s74
	s_nop 0
	global_load_lds_dwordx4 v[24:25], off
	s_waitcnt lgkmcnt(2)
	v_mfma_f32_16x16x32_f16 v[64:67], v[232:235], v[198:201], v[64:67]
	ds_read_b128 v[198:201], v134 offset:16384
	v_mfma_f32_16x16x32_f16 v[72:75], v[232:235], v[206:209], v[72:75]
	ds_read_b128 v[206:209], v134 offset:18432
	v_mfma_f32_16x16x32_f16 v[194:197], v[224:227], v[220:223], v[194:197]
	v_lshl_add_u64 v[28:29], v[122:123], 0, v[30:31]
	s_mov_b32 m0, s66
	s_nop 0
	global_load_lds_dwordx4 v[28:29], off
	v_mfma_f32_16x16x32_f16 v[84:87], v[224:227], v[228:231], v[84:87]
	ds_read_b128 v[224:227], v135 offset:53248
	v_mfma_f32_16x16x32_f16 v[80:83], v[232:235], v[220:223], v[80:83]
	ds_read_b128 v[220:223], v134 offset:20480
	v_mfma_f32_16x16x32_f16 v[88:91], v[232:235], v[228:231], v[88:91]
	ds_read_b128 v[228:231], v134 offset:22528
	ds_read_b128 v[232:235], v135 offset:55296
	s_waitcnt vmcnt(0) lgkmcnt(0)
	s_barrier
; #define GL_LOAD(s_, kt_) if (VAR != 1) { a##s_##0 = GL_A(0, kt_); a##s_##1 = GL_A(1, kt_); a##s_##2 = GL_A(2, kt_); a##s_##3 = GL_A(3, kt_); b##s_##0 = GL_B(0, kt_); b##s_##1 = GL_B(1, kt_); b##s_##2 = GL_B(2, kt_); b##s_##3 = GL_B(3, kt_); }
; #define LDS_STORE(s_, buf_) if (VAR != 2) { LDS_ST1(sA, 0, buf_, a##s_##0) LDS_ST1(sA, 1, buf_, a##s_##1) LDS_ST1(sA, 2, buf_, a##s_##2) LDS_ST1(sA, 3, buf_, a##s_##3) LDS_ST1(sB, 0, buf_, b##s_##0) LDS_ST1(sB, 1, buf_, b##s_##1) LDS_ST1(sB, 2, buf_, b##s_##2) LDS_ST1(sB, 3, buf_, b##s_##3) }
;     ...
;   for (int kt = 0; kt < nk; kt += 2) {
;     if (kt + 2 < nk) { GL_LOAD(0, kt + 2) }
;     MMA_TILE(0)
;     LDS_STORE(1, 1)
;     if (VAR != 4) __syncthreads();
;     if (kt + 3 < nk) { GL_LOAD(1, kt + 3) }
;     MMA_TILE(1)
;     if (kt + 2 < nk) { LDS_STORE(0, 0) }
;     if (VAR != 4) __syncthreads();
;   }
	v_mfma_f32_16x16x32_f16 v[138:141], v[202:205], v[198:201], v[138:141]
	v_mfma_f32_16x16x32_f16 v[92:95], v[202:205], v[206:209], v[92:95]
	v_mfma_f32_16x16x32_f16 v[142:145], v[210:213], v[198:201], v[142:145]
	v_mfma_f32_16x16x32_f16 v[158:161], v[210:213], v[206:209], v[158:161]
	v_mfma_f32_16x16x32_f16 v[166:169], v[202:205], v[220:223], v[166:169]
	v_mfma_f32_16x16x32_f16 v[68:71], v[202:205], v[228:231], v[68:71]
	ds_read_b128 v[202:205], v136 offset:32768
	v_mfma_f32_16x16x32_f16 v[190:193], v[210:213], v[220:223], v[190:193]
	v_mfma_f32_16x16x32_f16 v[76:79], v[210:213], v[228:231], v[76:79]
	ds_read_b128 v[210:213], v136 offset:34816
	v_mfma_f32_16x16x32_f16 v[154:157], v[224:227], v[198:201], v[154:157]
	v_mfma_f32_16x16x32_f16 v[162:165], v[224:227], v[206:209], v[162:165]
	v_mfma_f32_16x16x32_f16 v[64:67], v[232:235], v[198:201], v[64:67]
	ds_read_b128 v[198:201], v133
	v_mfma_f32_16x16x32_f16 v[72:75], v[232:235], v[206:209], v[72:75]
	ds_read_b128 v[206:209], v133 offset:2048
	v_mfma_f32_16x16x32_f16 v[194:197], v[224:227], v[220:223], v[194:197]
	v_and_b32_e32 v62, 7, v148
	v_bfe_u32 v63, v148, 4, 3
	v_xor_b32_e32 v63, v63, v62
	v_sub_u32_e32 v63, v63, v62
	v_lshlrev_b32_e32 v62, 4, v63
	v_add_u32_e32 v62, 0x380, v62
	v_ashrrev_i32_e32 v63, 31, v62
	v_mfma_f32_16x16x32_f16 v[84:87], v[224:227], v[228:231], v[84:87]
	ds_read_b128 v[224:227], v136 offset:36864
	v_mfma_f32_16x16x32_f16 v[80:83], v[232:235], v[220:223], v[80:83]
	ds_read_b128 v[220:223], v133 offset:4096
	v_mfma_f32_16x16x32_f16 v[88:91], v[232:235], v[228:231], v[88:91]
	ds_read_b128 v[228:231], v133 offset:6144
	s_waitcnt lgkmcnt(4)
	v_mfma_f32_16x16x32_f16 v[138:141], v[202:205], v[198:201], v[138:141]
	ds_read_b128 v[232:235], v136 offset:38912
	s_waitcnt lgkmcnt(4)
	v_mfma_f32_16x16x32_f16 v[92:95], v[202:205], v[206:209], v[92:95]
	v_lshl_add_u64 v[32:33], v[108:109], 0, v[62:63]
	s_mov_b32 m0, s61
	s_nop 0
	global_load_lds_dwordx4 v[32:33], off
	v_mfma_f32_16x16x32_f16 v[142:145], v[210:213], v[198:201], v[142:145]
	v_lshl_add_u64 v[36:37], v[110:111], 0, v[62:63]
	s_mov_b32 m0, s69
	s_nop 0
	global_load_lds_dwordx4 v[36:37], off
	v_mfma_f32_16x16x32_f16 v[158:161], v[210:213], v[206:209], v[158:161]
	v_lshl_add_u64 v[40:41], v[112:113], 0, v[62:63]
	s_mov_b32 m0, s73
	s_nop 0
	global_load_lds_dwordx4 v[40:41], off
	s_waitcnt lgkmcnt(2)
	v_mfma_f32_16x16x32_f16 v[166:169], v[202:205], v[220:223], v[166:169]
	v_lshl_add_u64 v[44:45], v[114:115], 0, v[62:63]
	s_mov_b32 m0, s65
	s_nop 0
	global_load_lds_dwordx4 v[44:45], off
	s_waitcnt lgkmcnt(1)
	v_mfma_f32_16x16x32_f16 v[68:71], v[202:205], v[228:231], v[68:71]
	ds_read_b128 v[202:205], v135 offset:32768
	v_mfma_f32_16x16x32_f16 v[190:193], v[210:213], v[220:223], v[190:193]
	v_lshl_add_u64 v[48:49], v[116:117], 0, v[62:63]
	s_mov_b32 m0, s63
	s_nop 0
	global_load_lds_dwordx4 v[48:49], off
	v_mfma_f32_16x16x32_f16 v[76:79], v[210:213], v[228:231], v[76:79]
	ds_read_b128 v[210:213], v135 offset:34816
	v_mfma_f32_16x16x32_f16 v[154:157], v[224:227], v[198:201], v[154:157]
	v_lshl_add_u64 v[52:53], v[118:119], 0, v[62:63]
	s_mov_b32 m0, s71
	s_nop 0
	global_load_lds_dwordx4 v[52:53], off
	v_mfma_f32_16x16x32_f16 v[162:165], v[224:227], v[206:209], v[162:165]
	v_lshl_add_u64 v[56:57], v[120:121], 0, v[62:63]
	s_mov_b32 m0, s75
	s_nop 0
	global_load_lds_dwordx4 v[56:57], off
	s_waitcnt lgkmcnt(2)
	v_mfma_f32_16x16x32_f16 v[64:67], v[232:235], v[198:201], v[64:67]
	ds_read_b128 v[198:201], v134
	v_mfma_f32_16x16x32_f16 v[72:75], v[232:235], v[206:209], v[72:75]
	ds_read_b128 v[206:209], v134 offset:2048
	v_mfma_f32_16x16x32_f16 v[194:197], v[224:227], v[220:223], v[194:197]
	v_lshl_add_u64 v[60:61], v[122:123], 0, v[62:63]
	s_mov_b32 m0, s67
	s_nop 0
	global_load_lds_dwordx4 v[60:61], off
	v_mfma_f32_16x16x32_f16 v[84:87], v[224:227], v[228:231], v[84:87]
	ds_read_b128 v[224:227], v135 offset:36864
	v_mfma_f32_16x16x32_f16 v[80:83], v[232:235], v[220:223], v[80:83]
	ds_read_b128 v[220:223], v134 offset:4096
	v_mfma_f32_16x16x32_f16 v[88:91], v[232:235], v[228:231], v[88:91]
	ds_read_b128 v[228:231], v134 offset:6144
	ds_read_b128 v[232:235], v135 offset:38912
	s_waitcnt vmcnt(0) lgkmcnt(0)
	s_barrier
	v_mfma_f32_16x16x32_f16 v[138:141], v[202:205], v[198:201], v[138:141]
	v_mfma_f32_16x16x32_f16 v[92:95], v[202:205], v[206:209], v[92:95]
	v_mfma_f32_16x16x32_f16 v[142:145], v[210:213], v[198:201], v[142:145]
	v_mfma_f32_16x16x32_f16 v[158:161], v[210:213], v[206:209], v[158:161]
	v_mfma_f32_16x16x32_f16 v[166:169], v[202:205], v[220:223], v[166:169]
	v_mfma_f32_16x16x32_f16 v[68:71], v[202:205], v[228:231], v[68:71]
	ds_read_b128 v[202:205], v136 offset:49152
	v_mfma_f32_16x16x32_f16 v[190:193], v[210:213], v[220:223], v[190:193]
	v_mfma_f32_16x16x32_f16 v[76:79], v[210:213], v[228:231], v[76:79]
	ds_read_b128 v[210:213], v136 offset:51200
	v_mfma_f32_16x16x32_f16 v[154:157], v[224:227], v[198:201], v[154:157]
	v_mfma_f32_16x16x32_f16 v[162:165], v[224:227], v[206:209], v[162:165]
	v_mfma_f32_16x16x32_f16 v[64:67], v[232:235], v[198:201], v[64:67]
	ds_read_b128 v[198:201], v133 offset:16384
	v_mfma_f32_16x16x32_f16 v[72:75], v[232:235], v[206:209], v[72:75]
	ds_read_b128 v[206:209], v133 offset:18432
	v_mfma_f32_16x16x32_f16 v[194:197], v[224:227], v[220:223], v[194:197]
	v_and_b32_e32 v30, 7, v148
	v_bfe_u32 v31, v148, 4, 3
	v_xor_b32_e32 v31, v31, v30
	v_sub_u32_e32 v31, v31, v30
	v_lshlrev_b32_e32 v30, 4, v31
	v_add_u32_e32 v30, 0x400, v30
	v_ashrrev_i32_e32 v31, 31, v30
	v_mfma_f32_16x16x32_f16 v[84:87], v[224:227], v[228:231], v[84:87]
	ds_read_b128 v[224:227], v136 offset:53248
	v_mfma_f32_16x16x32_f16 v[80:83], v[232:235], v[220:223], v[80:83]
	ds_read_b128 v[220:223], v133 offset:20480
	v_mfma_f32_16x16x32_f16 v[88:91], v[232:235], v[228:231], v[88:91]
	ds_read_b128 v[228:231], v133 offset:22528
	s_waitcnt lgkmcnt(4)
; #define GL_LOAD(s_, kt_) if (VAR != 1) { a##s_##0 = GL_A(0, kt_); a##s_##1 = GL_A(1, kt_); a##s_##2 = GL_A(2, kt_); a##s_##3 = GL_A(3, kt_); b##s_##0 = GL_B(0, kt_); b##s_##1 = GL_B(1, kt_); b##s_##2 = GL_B(2, kt_); b##s_##3 = GL_B(3, kt_); }
; #define LDS_STORE(s_, buf_) if (VAR != 2) { LDS_ST1(sA, 0, buf_, a##s_##0) LDS_ST1(sA, 1, buf_, a##s_##1) LDS_ST1(sA, 2, buf_, a##s_##2) LDS_ST1(sA, 3, buf_, a##s_##3) LDS_ST1(sB, 0, buf_, b##s_##0) LDS_ST1(sB, 1, buf_, b##s_##1) LDS_ST1(sB, 2, buf_, b##s_##2) LDS_ST1(sB, 3, buf_, b##s_##3) }
;     ...
;   for (int kt = 0; kt < nk; kt += 2) {
;     if (kt + 2 < nk) { GL_LOAD(0, kt + 2) }
;     MMA_TILE(0)
;     LDS_STORE(1, 1)
;     if (VAR != 4) __syncthreads();
;     if (kt + 3 < nk) { GL_LOAD(1, kt + 3) }
;     MMA_TILE(1)
;     if (kt + 2 < nk) { LDS_STORE(0, 0) }
;     if (VAR != 4) __syncthreads();
;   }
	v_mfma_f32_16x16x32_f16 v[138:141], v[202:205], v[198:201], v[138:141]
	ds_read_b128 v[232:235], v136 offset:55296
	s_waitcnt lgkmcnt(4)
	v_mfma_f32_16x16x32_f16 v[92:95], v[202:205], v[206:209], v[92:95]
	v_lshl_add_u64 v[0:1], v[108:109], 0, v[30:31]
	s_mov_b32 m0, s60
	s_nop 0
	global_load_lds_dwordx4 v[0:1], off
	v_mfma_f32_16x16x32_f16 v[142:145], v[210:213], v[198:201], v[142:145]
	v_lshl_add_u64 v[4:5], v[110:111], 0, v[30:31]
	s_mov_b32 m0, s68
	s_nop 0
	global_load_lds_dwordx4 v[4:5], off
	v_mfma_f32_16x16x32_f16 v[158:161], v[210:213], v[206:209], v[158:161]
	v_lshl_add_u64 v[8:9], v[112:113], 0, v[30:31]
	s_mov_b32 m0, s72
	s_nop 0
	global_load_lds_dwordx4 v[8:9], off
	s_waitcnt lgkmcnt(2)
	v_mfma_f32_16x16x32_f16 v[166:169], v[202:205], v[220:223], v[166:169]
	v_lshl_add_u64 v[12:13], v[114:115], 0, v[30:31]
	s_mov_b32 m0, s64
	s_nop 0
	global_load_lds_dwordx4 v[12:13], off
	s_waitcnt lgkmcnt(1)
	v_mfma_f32_16x16x32_f16 v[68:71], v[202:205], v[228:231], v[68:71]
	ds_read_b128 v[202:205], v135 offset:49152
	v_mfma_f32_16x16x32_f16 v[190:193], v[210:213], v[220:223], v[190:193]
	v_lshl_add_u64 v[16:17], v[116:117], 0, v[30:31]
	s_mov_b32 m0, s62
	s_nop 0
	global_load_lds_dwordx4 v[16:17], off
	v_mfma_f32_16x16x32_f16 v[76:79], v[210:213], v[228:231], v[76:79]
	ds_read_b128 v[210:213], v135 offset:51200
	v_mfma_f32_16x16x32_f16 v[154:157], v[224:227], v[198:201], v[154:157]
	v_lshl_add_u64 v[20:21], v[118:119], 0, v[30:31]
	s_mov_b32 m0, s70
	s_nop 0
	global_load_lds_dwordx4 v[20:21], off
	v_mfma_f32_16x16x32_f16 v[162:165], v[224:227], v[206:209], v[162:165]
	v_lshl_add_u64 v[24:25], v[120:121], 0, v[30:31]
	s_mov_b32 m0, s74
	s_nop 0
	global_load_lds_dwordx4 v[24:25], off
	s_waitcnt lgkmcnt(2)
	v_mfma_f32_16x16x32_f16 v[64:67], v[232:235], v[198:201], v[64:67]
	ds_read_b128 v[198:201], v134 offset:16384
	v_mfma_f32_16x16x32_f16 v[72:75], v[232:235], v[206:209], v[72:75]
	ds_read_b128 v[206:209], v134 offset:18432
	v_mfma_f32_16x16x32_f16 v[194:197], v[224:227], v[220:223], v[194:197]
	v_lshl_add_u64 v[28:29], v[122:123], 0, v[30:31]
	s_mov_b32 m0, s66
	s_nop 0
	global_load_lds_dwordx4 v[28:29], off
	v_mfma_f32_16x16x32_f16 v[84:87], v[224:227], v[228:231], v[84:87]
	ds_read_b128 v[224:227], v135 offset:53248
	v_mfma_f32_16x16x32_f16 v[80:83], v[232:235], v[220:223], v[80:83]
	ds_read_b128 v[220:223], v134 offset:20480
	v_mfma_f32_16x16x32_f16 v[88:91], v[232:235], v[228:231], v[88:91]
	ds_read_b128 v[228:231], v134 offset:22528
	s_waitcnt lgkmcnt(4)
	v_mfma_f32_16x16x32_f16 v[138:141], v[202:205], v[198:201], v[138:141]
	ds_read_b128 v[232:235], v135 offset:55296
	s_waitcnt vmcnt(0) lgkmcnt(0)
	s_barrier
	v_mfma_f32_16x16x32_f16 v[142:145], v[210:213], v[198:201], v[142:145]
	ds_read_b128 v[0:3], v133
	v_mfma_f32_16x16x32_f16 v[158:161], v[210:213], v[206:209], v[158:161]
	ds_read_b128 v[4:7], v136 offset:32768
	v_mfma_f32_16x16x32_f16 v[154:157], v[224:227], v[198:201], v[154:157]
	ds_read_b128 v[8:11], v133 offset:2048
	v_mfma_f32_16x16x32_f16 v[162:165], v[224:227], v[206:209], v[162:165]
	ds_read_b128 v[12:15], v136 offset:34816
	v_mfma_f32_16x16x32_f16 v[190:193], v[210:213], v[220:223], v[190:193]
	ds_read_b128 v[16:19], v133 offset:4096
	v_mfma_f32_16x16x32_f16 v[210:213], v[210:213], v[228:231], v[76:79]
	ds_read_b128 v[20:23], v136 offset:36864
	v_mfma_f32_16x16x32_f16 v[194:197], v[224:227], v[220:223], v[194:197]
	ds_read_b128 v[24:27], v133 offset:6144
	v_mfma_f32_16x16x32_f16 v[224:227], v[224:227], v[228:231], v[84:87]
	ds_read_b128 v[28:31], v136 offset:38912
	v_mfma_f32_16x16x32_f16 v[198:201], v[232:235], v[198:201], v[64:67]
	s_nop 2
	v_mfma_f32_16x16x32_f16 v[236:239], v[202:205], v[206:209], v[92:95]
	v_mfma_f32_16x16x32_f16 v[206:209], v[232:235], v[206:209], v[72:75]
	v_mfma_f32_16x16x32_f16 v[166:169], v[202:205], v[220:223], v[166:169]
	v_mfma_f32_16x16x32_f16 v[220:223], v[232:235], v[220:223], v[80:83]
	v_mfma_f32_16x16x32_f16 v[202:205], v[202:205], v[228:231], v[68:71]
	v_mfma_f32_16x16x32_f16 v[228:231], v[232:235], v[228:231], v[88:91]
	ds_read_b128 v[232:235], v135 offset:38912
	s_nop 0
	s_waitcnt lgkmcnt(7)
	v_mfma_f32_16x16x32_f16 v[138:141], v[4:7], v[0:3], v[138:141]
	s_waitcnt lgkmcnt(5)
	v_mfma_f32_16x16x32_f16 v[142:145], v[12:15], v[0:3], v[142:145]
	s_waitcnt lgkmcnt(3)
	v_mfma_f32_16x16x32_f16 v[154:157], v[20:23], v[0:3], v[154:157]
	s_waitcnt lgkmcnt(1)
	v_mfma_f32_16x16x32_f16 v[0:3], v[28:31], v[0:3], v[198:201]
	v_mfma_f32_16x16x32_f16 v[198:201], v[4:7], v[8:11], v[236:239]
	v_mfma_f32_16x16x32_f16 v[158:161], v[12:15], v[8:11], v[158:161]
	v_and_b32_e32 v62, 7, v148
	v_bfe_u32 v63, v148, 4, 3
	v_xor_b32_e32 v63, v63, v62
	v_sub_u32_e32 v63, v63, v62
	v_lshlrev_b32_e32 v62, 4, v63
	v_add_u32_e32 v62, 0x480, v62
	v_ashrrev_i32_e32 v63, 31, v62
	v_lshl_add_u64 v[32:33], v[108:109], 0, v[62:63]
	s_mov_b32 m0, s61
	s_nop 0
	global_load_lds_dwordx4 v[32:33], off
	v_mfma_f32_16x16x32_f16 v[166:169], v[4:7], v[16:19], v[166:169]
	v_lshl_add_u64 v[36:37], v[110:111], 0, v[62:63]
	s_mov_b32 m0, s69
	s_nop 0
	global_load_lds_dwordx4 v[36:37], off
	v_lshl_add_u64 v[40:41], v[112:113], 0, v[62:63]
	s_mov_b32 m0, s73
	s_nop 0
	global_load_lds_dwordx4 v[40:41], off
	v_mfma_f32_16x16x32_f16 v[4:7], v[4:7], v[24:27], v[202:205]
	s_nop 2
	ds_read_b128 v[202:205], v135 offset:32768
	v_lshl_add_u64 v[44:45], v[114:115], 0, v[62:63]
	s_mov_b32 m0, s65
	s_nop 0
	global_load_lds_dwordx4 v[44:45], off
	v_mfma_f32_16x16x32_f16 v[190:193], v[12:15], v[16:19], v[190:193]
	v_lshl_add_u64 v[48:49], v[116:117], 0, v[62:63]
	s_mov_b32 m0, s63
	s_nop 0
	global_load_lds_dwordx4 v[48:49], off
	v_mfma_f32_16x16x32_f16 v[12:15], v[12:15], v[24:27], v[210:213]
	s_nop 2
	ds_read_b128 v[210:213], v135 offset:34816
	v_lshl_add_u64 v[52:53], v[118:119], 0, v[62:63]
	s_mov_b32 m0, s71
	s_nop 0
	global_load_lds_dwordx4 v[52:53], off
	v_mfma_f32_16x16x32_f16 v[162:165], v[20:23], v[8:11], v[162:165]
	v_lshl_add_u64 v[56:57], v[120:121], 0, v[62:63]
	s_mov_b32 m0, s75
	s_nop 0
	global_load_lds_dwordx4 v[56:57], off
	v_lshl_add_u64 v[60:61], v[122:123], 0, v[62:63]
	s_mov_b32 m0, s67
	s_nop 0
	global_load_lds_dwordx4 v[60:61], off
	v_mfma_f32_16x16x32_f16 v[8:11], v[28:31], v[8:11], v[206:209]
	s_nop 2
	ds_read_b128 v[206:209], v134 offset:2048
	v_mfma_f32_16x16x32_f16 v[194:197], v[20:23], v[16:19], v[194:197]
	v_mfma_f32_16x16x32_f16 v[20:23], v[20:23], v[24:27], v[224:227]
	s_nop 2
	ds_read_b128 v[224:227], v135 offset:36864
	v_mfma_f32_16x16x32_f16 v[16:19], v[28:31], v[16:19], v[220:223]
	s_nop 2
	ds_read_b128 v[220:223], v134 offset:4096
	v_mfma_f32_16x16x32_f16 v[24:27], v[28:31], v[24:27], v[228:231]
	ds_read_b128 v[28:31], v134
	s_waitcnt lgkmcnt(0)
	v_mfma_f32_16x16x32_f16 v[138:141], v[202:205], v[28:31], v[138:141]
	ds_read_b128 v[228:231], v134 offset:6144
	s_waitcnt vmcnt(0) lgkmcnt(0)
	s_barrier
; #define GL_LOAD(s_, kt_) if (VAR != 1) { a##s_##0 = GL_A(0, kt_); a##s_##1 = GL_A(1, kt_); a##s_##2 = GL_A(2, kt_); a##s_##3 = GL_A(3, kt_); b##s_##0 = GL_B(0, kt_); b##s_##1 = GL_B(1, kt_); b##s_##2 = GL_B(2, kt_); b##s_##3 = GL_B(3, kt_); }
; #define LDS_STORE(s_, buf_) if (VAR != 2) { LDS_ST1(sA, 0, buf_, a##s_##0) LDS_ST1(sA, 1, buf_, a##s_##1) LDS_ST1(sA, 2, buf_, a##s_##2) LDS_ST1(sA, 3, buf_, a##s_##3) LDS_ST1(sB, 0, buf_, b##s_##0) LDS_ST1(sB, 1, buf_, b##s_##1) LDS_ST1(sB, 2, buf_, b##s_##2) LDS_ST1(sB, 3, buf_, b##s_##3) }
;     ...
;   for (int kt = 0; kt < nk; kt += 2) {
;     if (kt + 2 < nk) { GL_LOAD(0, kt + 2) }
;     MMA_TILE(0)
;     LDS_STORE(1, 1)
;     if (VAR != 4) __syncthreads();
;     if (kt + 3 < nk) { GL_LOAD(1, kt + 3) }
;     MMA_TILE(1)
;     if (kt + 2 < nk) { LDS_STORE(0, 0) }
;     if (VAR != 4) __syncthreads();
;   }
	v_mfma_f32_16x16x32_f16 v[142:145], v[210:213], v[28:31], v[142:145]
	ds_read_b128 v[32:35], v133 offset:16384
	v_mfma_f32_16x16x32_f16 v[158:161], v[210:213], v[206:209], v[158:161]
	ds_read_b128 v[36:39], v136 offset:49152
	v_mfma_f32_16x16x32_f16 v[154:157], v[224:227], v[28:31], v[154:157]
	ds_read_b128 v[40:43], v133 offset:18432
	v_mfma_f32_16x16x32_f16 v[162:165], v[224:227], v[206:209], v[162:165]
	ds_read_b128 v[44:47], v136 offset:51200
	v_mfma_f32_16x16x32_f16 v[190:193], v[210:213], v[220:223], v[190:193]
	ds_read_b128 v[48:51], v133 offset:20480
	v_mfma_f32_16x16x32_f16 v[210:213], v[210:213], v[228:231], v[12:15]
	ds_read_b128 v[52:55], v136 offset:53248
	v_mfma_f32_16x16x32_f16 v[194:197], v[224:227], v[220:223], v[194:197]
	ds_read_b128 v[56:59], v133 offset:22528
	v_mfma_f32_16x16x32_f16 v[224:227], v[224:227], v[228:231], v[20:23]
	ds_read_b128 v[60:63], v136 offset:55296
	v_mfma_f32_16x16x32_f16 v[236:239], v[232:235], v[28:31], v[0:3]
	v_mfma_f32_16x16x32_f16 v[198:201], v[202:205], v[206:209], v[198:201]
	v_mfma_f32_16x16x32_f16 v[206:209], v[232:235], v[206:209], v[8:11]
	v_mfma_f32_16x16x32_f16 v[166:169], v[202:205], v[220:223], v[166:169]
	v_mfma_f32_16x16x32_f16 v[220:223], v[232:235], v[220:223], v[16:19]
	v_mfma_f32_16x16x32_f16 v[202:205], v[202:205], v[228:231], v[4:7]
	v_mfma_f32_16x16x32_f16 v[228:231], v[232:235], v[228:231], v[24:27]
	ds_read_b128 v[232:235], v135 offset:55296
	s_nop 1
	s_waitcnt lgkmcnt(7)
	v_mfma_f32_16x16x32_f16 v[138:141], v[36:39], v[32:35], v[138:141]
	s_waitcnt lgkmcnt(6)
	v_mfma_f32_16x16x32_f16 v[198:201], v[36:39], v[40:43], v[198:201]
	s_waitcnt lgkmcnt(5)
	v_mfma_f32_16x16x32_f16 v[142:145], v[44:47], v[32:35], v[142:145]
	v_mfma_f32_16x16x32_f16 v[158:161], v[44:47], v[40:43], v[158:161]
	s_waitcnt lgkmcnt(4)
	v_mfma_f32_16x16x32_f16 v[166:169], v[36:39], v[48:51], v[166:169]
	v_and_b32_e32 v94, 7, v148
	v_bfe_u32 v95, v148, 4, 3
	v_xor_b32_e32 v95, v95, v94
	v_sub_u32_e32 v95, v95, v94
	v_lshlrev_b32_e32 v94, 4, v95
	v_add_u32_e32 v94, 0x500, v94
	v_ashrrev_i32_e32 v95, 31, v94
	s_waitcnt lgkmcnt(2)
	v_mfma_f32_16x16x32_f16 v[36:39], v[36:39], v[56:59], v[202:205]
	s_nop 2
	ds_read_b128 v[202:205], v135 offset:49152
	v_lshl_add_u64 v[64:65], v[108:109], 0, v[94:95]
	s_mov_b32 m0, s60
	s_nop 0
	global_load_lds_dwordx4 v[64:65], off
	v_mfma_f32_16x16x32_f16 v[190:193], v[44:47], v[48:51], v[190:193]
	v_lshl_add_u64 v[68:69], v[110:111], 0, v[94:95]
	s_mov_b32 m0, s68
	s_nop 0
	global_load_lds_dwordx4 v[68:69], off
	v_lshl_add_u64 v[72:73], v[112:113], 0, v[94:95]
	s_mov_b32 m0, s72
	s_nop 0
	global_load_lds_dwordx4 v[72:73], off
	v_mfma_f32_16x16x32_f16 v[44:47], v[44:47], v[56:59], v[210:213]
	s_nop 2
	ds_read_b128 v[210:213], v135 offset:51200
	v_mfma_f32_16x16x32_f16 v[154:157], v[52:55], v[32:35], v[154:157]
	v_lshl_add_u64 v[76:77], v[114:115], 0, v[94:95]
	s_mov_b32 m0, s64
	s_nop 0
	global_load_lds_dwordx4 v[76:77], off
	v_mfma_f32_16x16x32_f16 v[162:165], v[52:55], v[40:43], v[162:165]
	v_lshl_add_u64 v[80:81], v[116:117], 0, v[94:95]
	s_mov_b32 m0, s62
	s_nop 0
	global_load_lds_dwordx4 v[80:81], off
	s_waitcnt lgkmcnt(3)
	v_mfma_f32_16x16x32_f16 v[32:35], v[60:63], v[32:35], v[236:239]
	v_lshl_add_u64 v[84:85], v[118:119], 0, v[94:95]
	s_mov_b32 m0, s70
	s_nop 0
	global_load_lds_dwordx4 v[84:85], off
	v_mfma_f32_16x16x32_f16 v[40:43], v[60:63], v[40:43], v[206:209]
	s_nop 2
	ds_read_b128 v[206:209], v134 offset:18432
	v_mfma_f32_16x16x32_f16 v[194:197], v[52:55], v[48:51], v[194:197]
	v_lshl_add_u64 v[88:89], v[120:121], 0, v[94:95]
	s_mov_b32 m0, s74
	s_nop 0
	global_load_lds_dwordx4 v[88:89], off
	v_mfma_f32_16x16x32_f16 v[52:55], v[52:55], v[56:59], v[224:227]
	s_nop 2
	ds_read_b128 v[224:227], v135 offset:53248
	v_mfma_f32_16x16x32_f16 v[48:51], v[60:63], v[48:51], v[220:223]
	s_nop 2
	ds_read_b128 v[220:223], v134 offset:20480
	v_mfma_f32_16x16x32_f16 v[56:59], v[60:63], v[56:59], v[228:231]
	ds_read_b128 v[60:63], v134 offset:16384
	s_waitcnt lgkmcnt(0)
	v_mfma_f32_16x16x32_f16 v[138:141], v[202:205], v[60:63], v[138:141]
	ds_read_b128 v[228:231], v134 offset:22528
	v_lshl_add_u64 v[92:93], v[122:123], 0, v[94:95]
	s_mov_b32 m0, s66
	s_nop 0
	global_load_lds_dwordx4 v[92:93], off
	s_waitcnt vmcnt(0) lgkmcnt(0)
	s_barrier
; #define GL_LOAD(s_, kt_) if (VAR != 1) { a##s_##0 = GL_A(0, kt_); a##s_##1 = GL_A(1, kt_); a##s_##2 = GL_A(2, kt_); a##s_##3 = GL_A(3, kt_); b##s_##0 = GL_B(0, kt_); b##s_##1 = GL_B(1, kt_); b##s_##2 = GL_B(2, kt_); b##s_##3 = GL_B(3, kt_); }
; #define LDS_STORE(s_, buf_) if (VAR != 2) { LDS_ST1(sA, 0, buf_, a##s_##0) LDS_ST1(sA, 1, buf_, a##s_##1) LDS_ST1(sA, 2, buf_, a##s_##2) LDS_ST1(sA, 3, buf_, a##s_##3) LDS_ST1(sB, 0, buf_, b##s_##0) LDS_ST1(sB, 1, buf_, b##s_##1) LDS_ST1(sB, 2, buf_, b##s_##2) LDS_ST1(sB, 3, buf_, b##s_##3) }
;     ...
;   for (int kt = 0; kt < nk; kt += 2) {
;     if (kt + 2 < nk) { GL_LOAD(0, kt + 2) }
;     MMA_TILE(0)
;     LDS_STORE(1, 1)
;     if (VAR != 4) __syncthreads();
;     if (kt + 3 < nk) { GL_LOAD(1, kt + 3) }
;     MMA_TILE(1)
;     if (kt + 2 < nk) { LDS_STORE(0, 0) }
;     if (VAR != 4) __syncthreads();
;   }
	v_mfma_f32_16x16x32_f16 v[142:145], v[210:213], v[60:63], v[142:145]
	ds_read_b128 v[64:67], v133
	v_mfma_f32_16x16x32_f16 v[158:161], v[210:213], v[206:209], v[158:161]
	ds_read_b128 v[68:71], v136 offset:32768
	v_mfma_f32_16x16x32_f16 v[154:157], v[224:227], v[60:63], v[154:157]
	ds_read_b128 v[72:75], v133 offset:2048
	v_mfma_f32_16x16x32_f16 v[162:165], v[224:227], v[206:209], v[162:165]
	ds_read_b128 v[76:79], v136 offset:34816
	v_mfma_f32_16x16x32_f16 v[190:193], v[210:213], v[220:223], v[190:193]
	ds_read_b128 v[80:83], v133 offset:4096
	v_mfma_f32_16x16x32_f16 v[210:213], v[210:213], v[228:231], v[44:47]
	ds_read_b128 v[84:87], v136 offset:36864
	v_mfma_f32_16x16x32_f16 v[194:197], v[224:227], v[220:223], v[194:197]
	ds_read_b128 v[88:91], v133 offset:6144
	v_mfma_f32_16x16x32_f16 v[224:227], v[224:227], v[228:231], v[52:55]
	ds_read_b128 v[92:95], v136 offset:38912
	v_mfma_f32_16x16x32_f16 v[236:239], v[232:235], v[60:63], v[32:35]
	s_nop 0
	v_mfma_f32_16x16x32_f16 v[198:201], v[202:205], v[206:209], v[198:201]
	v_mfma_f32_16x16x32_f16 v[206:209], v[232:235], v[206:209], v[40:43]
	v_mfma_f32_16x16x32_f16 v[166:169], v[202:205], v[220:223], v[166:169]
	v_mfma_f32_16x16x32_f16 v[220:223], v[232:235], v[220:223], v[48:51]
	v_mfma_f32_16x16x32_f16 v[202:205], v[202:205], v[228:231], v[36:39]
	v_mfma_f32_16x16x32_f16 v[228:231], v[232:235], v[228:231], v[56:59]
	ds_read_b128 v[232:235], v135 offset:38912
	s_nop 1
	s_waitcnt lgkmcnt(7)
	v_mfma_f32_16x16x32_f16 v[138:141], v[68:71], v[64:67], v[138:141]
	s_waitcnt lgkmcnt(6)
	v_mfma_f32_16x16x32_f16 v[198:201], v[68:71], v[72:75], v[198:201]
	s_waitcnt lgkmcnt(5)
	v_mfma_f32_16x16x32_f16 v[142:145], v[76:79], v[64:67], v[142:145]
	v_mfma_f32_16x16x32_f16 v[158:161], v[76:79], v[72:75], v[158:161]
	s_waitcnt lgkmcnt(4)
	v_mfma_f32_16x16x32_f16 v[166:169], v[68:71], v[80:83], v[166:169]
	v_and_b32_e32 v10, 7, v148
	v_bfe_u32 v11, v148, 4, 3
	v_xor_b32_e32 v11, v11, v10
	v_sub_u32_e32 v11, v11, v10
	v_lshlrev_b32_e32 v10, 4, v11
	v_add_u32_e32 v10, 0x580, v10
	v_ashrrev_i32_e32 v11, 31, v10
	v_lshl_add_u64 v[28:29], v[108:109], 0, v[10:11]
	s_mov_b32 m0, s61
	s_nop 0
	global_load_lds_dwordx4 v[28:29], off
	s_waitcnt lgkmcnt(2)
	v_mfma_f32_16x16x32_f16 v[68:71], v[68:71], v[88:91], v[202:205]
	s_nop 2
	ds_read_b128 v[202:205], v135 offset:32768
	v_lshl_add_u64 v[24:25], v[110:111], 0, v[10:11]
	s_mov_b32 m0, s69
	s_nop 0
	global_load_lds_dwordx4 v[24:25], off
	v_mfma_f32_16x16x32_f16 v[190:193], v[76:79], v[80:83], v[190:193]
	v_lshl_add_u64 v[12:13], v[112:113], 0, v[10:11]
	s_mov_b32 m0, s73
	s_nop 0
	global_load_lds_dwordx4 v[12:13], off
	v_lshl_add_u64 v[16:17], v[114:115], 0, v[10:11]
	s_mov_b32 m0, s65
	s_nop 0
	global_load_lds_dwordx4 v[16:17], off
	v_mfma_f32_16x16x32_f16 v[76:79], v[76:79], v[88:91], v[210:213]
	s_nop 2
	ds_read_b128 v[210:213], v135 offset:34816
	v_mfma_f32_16x16x32_f16 v[154:157], v[84:87], v[64:67], v[154:157]
	v_lshl_add_u64 v[20:21], v[116:117], 0, v[10:11]
	s_mov_b32 m0, s63
	s_nop 0
	global_load_lds_dwordx4 v[20:21], off
	v_mfma_f32_16x16x32_f16 v[162:165], v[84:87], v[72:75], v[162:165]
	v_lshl_add_u64 v[0:1], v[118:119], 0, v[10:11]
	s_mov_b32 m0, s71
	s_nop 0
	global_load_lds_dwordx4 v[0:1], off
	s_waitcnt lgkmcnt(3)
	v_mfma_f32_16x16x32_f16 v[64:67], v[92:95], v[64:67], v[236:239]
	v_lshl_add_u64 v[4:5], v[120:121], 0, v[10:11]
	s_mov_b32 m0, s75
	s_nop 0
	global_load_lds_dwordx4 v[4:5], off
	v_mfma_f32_16x16x32_f16 v[72:75], v[92:95], v[72:75], v[206:209]
	s_nop 2
	ds_read_b128 v[206:209], v134 offset:2048
	v_mfma_f32_16x16x32_f16 v[194:197], v[84:87], v[80:83], v[194:197]
	v_lshl_add_u64 v[8:9], v[122:123], 0, v[10:11]
	s_mov_b32 m0, s67
	s_nop 0
	global_load_lds_dwordx4 v[8:9], off
	v_mfma_f32_16x16x32_f16 v[84:87], v[84:87], v[88:91], v[224:227]
	s_nop 2
	ds_read_b128 v[224:227], v135 offset:36864
	v_mfma_f32_16x16x32_f16 v[80:83], v[92:95], v[80:83], v[220:223]
	s_nop 2
	ds_read_b128 v[220:223], v134 offset:4096
	v_mfma_f32_16x16x32_f16 v[88:91], v[92:95], v[88:91], v[228:231]
	ds_read_b128 v[92:95], v134
	s_nop 1
	ds_read_b128 v[228:231], v134 offset:6144
	s_waitcnt vmcnt(0) lgkmcnt(0)
	s_barrier
	v_mfma_f32_16x16x32_f16 v[138:141], v[202:205], v[92:95], v[138:141]
	v_mfma_f32_16x16x32_f16 v[142:145], v[210:213], v[92:95], v[142:145]
	v_mfma_f32_16x16x32_f16 v[154:157], v[224:227], v[92:95], v[154:157]
	v_mfma_f32_16x16x32_f16 v[64:67], v[232:235], v[92:95], v[64:67]
	v_mfma_f32_16x16x32_f16 v[92:95], v[202:205], v[206:209], v[198:201]
	s_nop 2
	ds_read_b128 v[198:201], v133 offset:16384
	v_mfma_f32_16x16x32_f16 v[158:161], v[210:213], v[206:209], v[158:161]
	v_mfma_f32_16x16x32_f16 v[166:169], v[202:205], v[220:223], v[166:169]
	v_mfma_f32_16x16x32_f16 v[68:71], v[202:205], v[228:231], v[68:71]
	ds_read_b128 v[202:205], v136 offset:49152
	v_mfma_f32_16x16x32_f16 v[190:193], v[210:213], v[220:223], v[190:193]
	v_mfma_f32_16x16x32_f16 v[76:79], v[210:213], v[228:231], v[76:79]
	ds_read_b128 v[210:213], v136 offset:51200
	v_mfma_f32_16x16x32_f16 v[162:165], v[224:227], v[206:209], v[162:165]
	v_mfma_f32_16x16x32_f16 v[72:75], v[232:235], v[206:209], v[72:75]
	ds_read_b128 v[206:209], v133 offset:18432
	v_mfma_f32_16x16x32_f16 v[194:197], v[224:227], v[220:223], v[194:197]
	v_and_b32_e32 v38, 7, v148
	v_bfe_u32 v39, v148, 4, 3
	v_xor_b32_e32 v39, v39, v38
	v_sub_u32_e32 v39, v39, v38
	v_lshlrev_b32_e32 v38, 4, v39
	v_add_u32_e32 v38, 0x600, v38
	v_ashrrev_i32_e32 v39, 31, v38
	v_mfma_f32_16x16x32_f16 v[84:87], v[224:227], v[228:231], v[84:87]
	ds_read_b128 v[224:227], v136 offset:53248
	v_mfma_f32_16x16x32_f16 v[80:83], v[232:235], v[220:223], v[80:83]
	ds_read_b128 v[220:223], v133 offset:20480
	v_mfma_f32_16x16x32_f16 v[88:91], v[232:235], v[228:231], v[88:91]
	ds_read_b128 v[228:231], v133 offset:22528
	s_waitcnt lgkmcnt(5)
; #define GL_LOAD(s_, kt_) if (VAR != 1) { a##s_##0 = GL_A(0, kt_); a##s_##1 = GL_A(1, kt_); a##s_##2 = GL_A(2, kt_); a##s_##3 = GL_A(3, kt_); b##s_##0 = GL_B(0, kt_); b##s_##1 = GL_B(1, kt_); b##s_##2 = GL_B(2, kt_); b##s_##3 = GL_B(3, kt_); }
; #define LDS_STORE(s_, buf_) if (VAR != 2) { LDS_ST1(sA, 0, buf_, a##s_##0) LDS_ST1(sA, 1, buf_, a##s_##1) LDS_ST1(sA, 2, buf_, a##s_##2) LDS_ST1(sA, 3, buf_, a##s_##3) LDS_ST1(sB, 0, buf_, b##s_##0) LDS_ST1(sB, 1, buf_, b##s_##1) LDS_ST1(sB, 2, buf_, b##s_##2) LDS_ST1(sB, 3, buf_, b##s_##3) }
;     ...
;   for (int kt = 0; kt < nk; kt += 2) {
;     if (kt + 2 < nk) { GL_LOAD(0, kt + 2) }
;     MMA_TILE(0)
;     LDS_STORE(1, 1)
;     if (VAR != 4) __syncthreads();
;     if (kt + 3 < nk) { GL_LOAD(1, kt + 3) }
;     MMA_TILE(1)
;     if (kt + 2 < nk) { LDS_STORE(0, 0) }
;     if (VAR != 4) __syncthreads();
;   }
	v_mfma_f32_16x16x32_f16 v[138:141], v[202:205], v[198:201], v[138:141]
	ds_read_b128 v[232:235], v136 offset:55296
	s_waitcnt lgkmcnt(4)
	v_mfma_f32_16x16x32_f16 v[92:95], v[202:205], v[206:209], v[92:95]
	v_lshl_add_u64 v[52:53], v[108:109], 0, v[38:39]
	s_mov_b32 m0, s60
	s_nop 0
	global_load_lds_dwordx4 v[52:53], off
	v_mfma_f32_16x16x32_f16 v[142:145], v[210:213], v[198:201], v[142:145]
	v_lshl_add_u64 v[56:57], v[110:111], 0, v[38:39]
	s_mov_b32 m0, s68
	s_nop 0
	global_load_lds_dwordx4 v[56:57], off
	v_mfma_f32_16x16x32_f16 v[158:161], v[210:213], v[206:209], v[158:161]
	v_lshl_add_u64 v[60:61], v[112:113], 0, v[38:39]
	s_mov_b32 m0, s72
	s_nop 0
	global_load_lds_dwordx4 v[60:61], off
	s_waitcnt lgkmcnt(2)
	v_mfma_f32_16x16x32_f16 v[166:169], v[202:205], v[220:223], v[166:169]
	v_lshl_add_u64 v[40:41], v[114:115], 0, v[38:39]
	s_mov_b32 m0, s64
	s_nop 0
	global_load_lds_dwordx4 v[40:41], off
	s_waitcnt lgkmcnt(1)
	v_mfma_f32_16x16x32_f16 v[68:71], v[202:205], v[228:231], v[68:71]
	ds_read_b128 v[202:205], v135 offset:49152
	v_mfma_f32_16x16x32_f16 v[190:193], v[210:213], v[220:223], v[190:193]
	v_lshl_add_u64 v[44:45], v[116:117], 0, v[38:39]
	s_mov_b32 m0, s62
	s_nop 0
	global_load_lds_dwordx4 v[44:45], off
	v_mfma_f32_16x16x32_f16 v[76:79], v[210:213], v[228:231], v[76:79]
	ds_read_b128 v[210:213], v135 offset:51200
	v_mfma_f32_16x16x32_f16 v[154:157], v[224:227], v[198:201], v[154:157]
	v_lshl_add_u64 v[48:49], v[118:119], 0, v[38:39]
	s_mov_b32 m0, s70
	s_nop 0
	global_load_lds_dwordx4 v[48:49], off
	v_mfma_f32_16x16x32_f16 v[162:165], v[224:227], v[206:209], v[162:165]
	v_lshl_add_u64 v[32:33], v[120:121], 0, v[38:39]
	s_mov_b32 m0, s74
	s_nop 0
	global_load_lds_dwordx4 v[32:33], off
	s_waitcnt lgkmcnt(2)
	v_mfma_f32_16x16x32_f16 v[64:67], v[232:235], v[198:201], v[64:67]
	ds_read_b128 v[198:201], v134 offset:16384
	v_mfma_f32_16x16x32_f16 v[72:75], v[232:235], v[206:209], v[72:75]
	ds_read_b128 v[206:209], v134 offset:18432
	v_mfma_f32_16x16x32_f16 v[194:197], v[224:227], v[220:223], v[194:197]
	v_lshl_add_u64 v[36:37], v[122:123], 0, v[38:39]
	s_mov_b32 m0, s66
	s_nop 0
	global_load_lds_dwordx4 v[36:37], off
	v_mfma_f32_16x16x32_f16 v[84:87], v[224:227], v[228:231], v[84:87]
	ds_read_b128 v[224:227], v135 offset:53248
	v_mfma_f32_16x16x32_f16 v[80:83], v[232:235], v[220:223], v[80:83]
	ds_read_b128 v[220:223], v134 offset:20480
	v_mfma_f32_16x16x32_f16 v[88:91], v[232:235], v[228:231], v[88:91]
	ds_read_b128 v[228:231], v134 offset:22528
	ds_read_b128 v[232:235], v135 offset:55296
	s_waitcnt vmcnt(0) lgkmcnt(0)
	s_barrier
	v_mfma_f32_16x16x32_f16 v[138:141], v[202:205], v[198:201], v[138:141]
	v_and_b32_e32 v6, 7, v148
	v_bfe_u32 v7, v148, 4, 3
	v_xor_b32_e32 v7, v7, v6
	v_sub_u32_e32 v7, v7, v6
	v_lshlrev_b32_e32 v6, 4, v7
	v_add_u32_e32 v6, 0x680, v6
	v_ashrrev_i32_e32 v7, 31, v6
	v_mfma_f32_16x16x32_f16 v[92:95], v[202:205], v[206:209], v[92:95]
	global_load_dwordx4 v[60:63], v[108:109], off offset:1792
	v_mfma_f32_16x16x32_f16 v[142:145], v[210:213], v[198:201], v[142:145]
	global_load_dwordx4 v[48:51], v[110:111], off offset:1792
	v_mfma_f32_16x16x32_f16 v[158:161], v[210:213], v[206:209], v[158:161]
	global_load_dwordx4 v[52:55], v[112:113], off offset:1792
	v_mfma_f32_16x16x32_f16 v[166:169], v[202:205], v[220:223], v[166:169]
	global_load_dwordx4 v[56:59], v[114:115], off offset:1792
	v_mfma_f32_16x16x32_f16 v[68:71], v[202:205], v[228:231], v[68:71]
	ds_read_b128 v[202:205], v136 offset:32768
	v_mfma_f32_16x16x32_f16 v[190:193], v[210:213], v[220:223], v[190:193]
	global_load_dwordx4 v[36:39], v[116:117], off offset:1792
	v_mfma_f32_16x16x32_f16 v[76:79], v[210:213], v[228:231], v[76:79]
	ds_read_b128 v[210:213], v136 offset:34816
	v_mfma_f32_16x16x32_f16 v[154:157], v[224:227], v[198:201], v[154:157]
	global_load_dwordx4 v[40:43], v[118:119], off offset:1792
	v_mfma_f32_16x16x32_f16 v[162:165], v[224:227], v[206:209], v[162:165]
	global_load_dwordx4 v[44:47], v[120:121], off offset:1792
	v_mfma_f32_16x16x32_f16 v[64:67], v[232:235], v[198:201], v[64:67]
	ds_read_b128 v[198:201], v133
	v_mfma_f32_16x16x32_f16 v[72:75], v[232:235], v[206:209], v[72:75]
	ds_read_b128 v[206:209], v133 offset:2048
	v_mfma_f32_16x16x32_f16 v[194:197], v[224:227], v[220:223], v[194:197]
	global_load_dwordx4 v[32:35], v[122:123], off offset:1792
	v_mfma_f32_16x16x32_f16 v[84:87], v[224:227], v[228:231], v[84:87]
	ds_read_b128 v[224:227], v136 offset:36864
	v_mfma_f32_16x16x32_f16 v[80:83], v[232:235], v[220:223], v[80:83]
	ds_read_b128 v[220:223], v133 offset:4096
	v_mfma_f32_16x16x32_f16 v[88:91], v[232:235], v[228:231], v[88:91]
	ds_read_b128 v[228:231], v133 offset:6144
	s_waitcnt lgkmcnt(4)
	v_mfma_f32_16x16x32_f16 v[138:141], v[202:205], v[198:201], v[138:141]
	ds_read_b128 v[232:235], v136 offset:38912
	s_waitcnt lgkmcnt(4)
	v_mfma_f32_16x16x32_f16 v[92:95], v[202:205], v[206:209], v[92:95]
	v_lshl_add_u64 v[20:21], v[108:109], 0, v[6:7]
	s_mov_b32 m0, s61
	s_nop 0
	global_load_lds_dwordx4 v[20:21], off
	v_mfma_f32_16x16x32_f16 v[142:145], v[210:213], v[198:201], v[142:145]
	v_lshl_add_u64 v[24:25], v[110:111], 0, v[6:7]
	s_mov_b32 m0, s69
	s_nop 0
	global_load_lds_dwordx4 v[24:25], off
	v_mfma_f32_16x16x32_f16 v[158:161], v[210:213], v[206:209], v[158:161]
	v_lshl_add_u64 v[28:29], v[112:113], 0, v[6:7]
	s_mov_b32 m0, s73
	s_nop 0
	global_load_lds_dwordx4 v[28:29], off
	s_waitcnt lgkmcnt(2)
	v_mfma_f32_16x16x32_f16 v[166:169], v[202:205], v[220:223], v[166:169]
	v_lshl_add_u64 v[8:9], v[114:115], 0, v[6:7]
	s_mov_b32 m0, s65
	s_nop 0
	global_load_lds_dwordx4 v[8:9], off
	s_waitcnt lgkmcnt(1)
; #define GL_LOAD(s_, kt_) if (VAR != 1) { a##s_##0 = GL_A(0, kt_); a##s_##1 = GL_A(1, kt_); a##s_##2 = GL_A(2, kt_); a##s_##3 = GL_A(3, kt_); b##s_##0 = GL_B(0, kt_); b##s_##1 = GL_B(1, kt_); b##s_##2 = GL_B(2, kt_); b##s_##3 = GL_B(3, kt_); }
; #define LDS_STORE(s_, buf_) if (VAR != 2) { LDS_ST1(sA, 0, buf_, a##s_##0) LDS_ST1(sA, 1, buf_, a##s_##1) LDS_ST1(sA, 2, buf_, a##s_##2) LDS_ST1(sA, 3, buf_, a##s_##3) LDS_ST1(sB, 0, buf_, b##s_##0) LDS_ST1(sB, 1, buf_, b##s_##1) LDS_ST1(sB, 2, buf_, b##s_##2) LDS_ST1(sB, 3, buf_, b##s_##3) }
;     ...
;   for (int kt = 0; kt < nk; kt += 2) {
;     if (kt + 2 < nk) { GL_LOAD(0, kt + 2) }
;     MMA_TILE(0)
;     LDS_STORE(1, 1)
;     if (VAR != 4) __syncthreads();
;     if (kt + 3 < nk) { GL_LOAD(1, kt + 3) }
;     MMA_TILE(1)
;     if (kt + 2 < nk) { LDS_STORE(0, 0) }
;     if (VAR != 4) __syncthreads();
;   }
	v_mfma_f32_16x16x32_f16 v[68:71], v[202:205], v[228:231], v[68:71]
	ds_read_b128 v[202:205], v135 offset:32768
	v_mfma_f32_16x16x32_f16 v[190:193], v[210:213], v[220:223], v[190:193]
	v_lshl_add_u64 v[12:13], v[116:117], 0, v[6:7]
	s_mov_b32 m0, s63
	s_nop 0
	global_load_lds_dwordx4 v[12:13], off
	v_mfma_f32_16x16x32_f16 v[76:79], v[210:213], v[228:231], v[76:79]
	ds_read_b128 v[210:213], v135 offset:34816
	v_mfma_f32_16x16x32_f16 v[154:157], v[224:227], v[198:201], v[154:157]
	v_lshl_add_u64 v[16:17], v[118:119], 0, v[6:7]
	s_mov_b32 m0, s71
	s_nop 0
	global_load_lds_dwordx4 v[16:17], off
	v_mfma_f32_16x16x32_f16 v[162:165], v[224:227], v[206:209], v[162:165]
	v_lshl_add_u64 v[0:1], v[120:121], 0, v[6:7]
	s_mov_b32 m0, s75
	s_nop 0
	global_load_lds_dwordx4 v[0:1], off
	s_waitcnt lgkmcnt(2)
	v_mfma_f32_16x16x32_f16 v[64:67], v[232:235], v[198:201], v[64:67]
	ds_read_b128 v[198:201], v134
	v_mfma_f32_16x16x32_f16 v[72:75], v[232:235], v[206:209], v[72:75]
	ds_read_b128 v[206:209], v134 offset:2048
	v_mfma_f32_16x16x32_f16 v[194:197], v[224:227], v[220:223], v[194:197]
	v_lshl_add_u64 v[4:5], v[122:123], 0, v[6:7]
	s_mov_b32 m0, s67
	s_nop 0
	global_load_lds_dwordx4 v[4:5], off
	v_mfma_f32_16x16x32_f16 v[84:87], v[224:227], v[228:231], v[84:87]
	ds_read_b128 v[224:227], v135 offset:36864
	v_mfma_f32_16x16x32_f16 v[80:83], v[232:235], v[220:223], v[80:83]
	ds_read_b128 v[220:223], v134 offset:4096
	v_mfma_f32_16x16x32_f16 v[88:91], v[232:235], v[228:231], v[88:91]
	ds_read_b128 v[228:231], v134 offset:6144
	ds_read_b128 v[232:235], v135 offset:38912
	s_waitcnt vmcnt(0) lgkmcnt(0)
	s_barrier
	v_mfma_f32_16x16x32_f16 v[138:141], v[202:205], v[198:201], v[138:141]
	global_load_dwordx4 v[28:31], v[108:109], off offset:1920
	v_mfma_f32_16x16x32_f16 v[92:95], v[202:205], v[206:209], v[92:95]
	global_load_dwordx4 v[16:19], v[110:111], off offset:1920
	v_mfma_f32_16x16x32_f16 v[142:145], v[210:213], v[198:201], v[142:145]
	ds_read_b128 v[108:111], v133 offset:16384
	v_mfma_f32_16x16x32_f16 v[158:161], v[210:213], v[206:209], v[158:161]
	global_load_dwordx4 v[20:23], v[112:113], off offset:1920
	v_mfma_f32_16x16x32_f16 v[166:169], v[202:205], v[220:223], v[166:169]
	global_load_dwordx4 v[24:27], v[114:115], off offset:1920
	v_mfma_f32_16x16x32_f16 v[68:71], v[202:205], v[228:231], v[68:71]
	ds_read_b128 v[112:115], v136 offset:49152
	v_mfma_f32_16x16x32_f16 v[190:193], v[210:213], v[220:223], v[190:193]
	ds_read_b128 v[202:205], v136 offset:53248
	v_mfma_f32_16x16x32_f16 v[76:79], v[210:213], v[228:231], v[76:79]
	ds_read_b128 v[210:213], v136 offset:55296
	v_mfma_f32_16x16x32_f16 v[154:157], v[224:227], v[198:201], v[154:157]
	global_load_dwordx4 v[4:7], v[116:117], off offset:1920
	v_mfma_f32_16x16x32_f16 v[162:165], v[224:227], v[206:209], v[162:165]
	global_load_dwordx4 v[8:11], v[118:119], off offset:1920
	v_mfma_f32_16x16x32_f16 v[64:67], v[232:235], v[198:201], v[64:67]
	ds_read_b128 v[116:119], v133 offset:18432
	v_mfma_f32_16x16x32_f16 v[72:75], v[232:235], v[206:209], v[72:75]
	ds_read_b128 v[198:201], v133 offset:20480
	v_mfma_f32_16x16x32_f16 v[194:197], v[224:227], v[220:223], v[194:197]
	ds_read_b128 v[206:209], v133 offset:22528
	v_mfma_f32_16x16x32_f16 v[84:87], v[224:227], v[228:231], v[84:87]
	global_load_dwordx4 v[12:15], v[120:121], off offset:1920
	v_mfma_f32_16x16x32_f16 v[80:83], v[232:235], v[220:223], v[80:83]
	global_load_dwordx4 v[0:3], v[122:123], off offset:1920
	v_mfma_f32_16x16x32_f16 v[88:91], v[232:235], v[228:231], v[88:91]
	ds_read_b128 v[120:123], v136 offset:51200
	s_waitcnt lgkmcnt(6)
	v_mfma_f32_16x16x32_f16 v[138:141], v[112:115], v[108:111], v[138:141]
	ds_write_b128 v101, v[60:63]
	s_waitcnt lgkmcnt(4)
	v_mfma_f32_16x16x32_f16 v[92:95], v[112:115], v[116:119], v[92:95]
	ds_write_b128 v131, v[48:51]
	s_waitcnt lgkmcnt(2)
	v_mfma_f32_16x16x32_f16 v[142:145], v[120:123], v[108:111], v[142:145]
	ds_write_b128 v132, v[52:55]
	v_mfma_f32_16x16x32_f16 v[154:157], v[202:205], v[108:111], v[154:157]
	v_mfma_f32_16x16x32_f16 v[64:67], v[210:213], v[108:111], v[64:67]
	v_mfma_f32_16x16x32_f16 v[108:111], v[120:123], v[116:119], v[158:161]
	ds_write_b128 v130, v[56:59]
	v_mfma_f32_16x16x32_f16 v[158:161], v[202:205], v[116:119], v[162:165]
	v_mfma_f32_16x16x32_f16 v[72:75], v[210:213], v[116:119], v[72:75]
	v_mfma_f32_16x16x32_f16 v[116:119], v[112:115], v[198:201], v[166:169]
	ds_write_b128 v101, v[36:39] offset:32768
	ds_write_b128 v131, v[40:43] offset:32768
	v_mfma_f32_16x16x32_f16 v[68:71], v[112:115], v[206:209], v[68:71]
	ds_read_b128 v[112:115], v134 offset:16384
	ds_write_b128 v132, v[44:47] offset:32768
	v_mfma_f32_16x16x32_f16 v[162:165], v[120:123], v[198:201], v[190:193]
	s_nop 2
	ds_read_b128 v[190:193], v134 offset:18432
	v_mfma_f32_16x16x32_f16 v[76:79], v[120:123], v[206:209], v[76:79]
	ds_read_b128 v[120:123], v135 offset:49152
	ds_write_b128 v130, v[32:35] offset:32768
	v_mfma_f32_16x16x32_f16 v[166:169], v[202:205], v[198:201], v[194:197]
	s_nop 2
	ds_read_b128 v[194:197], v135 offset:51200
	v_mfma_f32_16x16x32_f16 v[84:87], v[202:205], v[206:209], v[84:87]
	ds_read_b128 v[202:205], v135 offset:53248
	v_mfma_f32_16x16x32_f16 v[80:83], v[210:213], v[198:201], v[80:83]
	ds_read_b128 v[198:201], v134 offset:20480
	v_mfma_f32_16x16x32_f16 v[88:91], v[210:213], v[206:209], v[88:91]
	ds_read_b128 v[206:209], v134 offset:22528
	s_waitcnt lgkmcnt(5)
	v_mfma_f32_16x16x32_f16 v[138:141], v[120:123], v[112:115], v[138:141]
	ds_read_b128 v[210:213], v135 offset:55296
	s_waitcnt lgkmcnt(0)
	s_barrier
; #define GL_LOAD(s_, kt_) if (VAR != 1) { a##s_##0 = GL_A(0, kt_); a##s_##1 = GL_A(1, kt_); a##s_##2 = GL_A(2, kt_); a##s_##3 = GL_A(3, kt_); b##s_##0 = GL_B(0, kt_); b##s_##1 = GL_B(1, kt_); b##s_##2 = GL_B(2, kt_); b##s_##3 = GL_B(3, kt_); }
; #define LDS_STORE(s_, buf_) if (VAR != 2) { LDS_ST1(sA, 0, buf_, a##s_##0) LDS_ST1(sA, 1, buf_, a##s_##1) LDS_ST1(sA, 2, buf_, a##s_##2) LDS_ST1(sA, 3, buf_, a##s_##3) LDS_ST1(sB, 0, buf_, b##s_##0) LDS_ST1(sB, 1, buf_, b##s_##1) LDS_ST1(sB, 2, buf_, b##s_##2) LDS_ST1(sB, 3, buf_, b##s_##3) }
;     ...
;     MMA_TILE(0)
;     LDS_STORE(1, 1)
;     if (VAR != 4) __syncthreads();
;     if (kt + 3 < nk) { GL_LOAD(1, kt + 3) }
;     MMA_TILE(1)
;     if (kt + 2 < nk) { LDS_STORE(0, 0) }
;     if (VAR != 4) __syncthreads();
	v_mfma_f32_16x16x32_f16 v[142:145], v[194:197], v[112:115], v[142:145]
	ds_read_b128 v[32:35], v133
	v_mfma_f32_16x16x32_f16 v[108:111], v[194:197], v[190:193], v[108:111]
	ds_read_b128 v[36:39], v136 offset:32768
	v_mfma_f32_16x16x32_f16 v[154:157], v[202:205], v[112:115], v[154:157]
	ds_read_b128 v[40:43], v133 offset:2048
	v_mfma_f32_16x16x32_f16 v[64:67], v[210:213], v[112:115], v[64:67]
	v_mfma_f32_16x16x32_f16 v[112:115], v[202:205], v[190:193], v[158:161]
	ds_read_b128 v[44:47], v136 offset:34816
	v_mfma_f32_16x16x32_f16 v[158:161], v[194:197], v[198:201], v[162:165]
	ds_read_b128 v[48:51], v133 offset:4096
	v_mfma_f32_16x16x32_f16 v[76:79], v[194:197], v[206:209], v[76:79]
	ds_read_b128 v[52:55], v136 offset:36864
	v_mfma_f32_16x16x32_f16 v[162:165], v[202:205], v[198:201], v[166:169]
	ds_read_b128 v[56:59], v133 offset:6144
	v_mfma_f32_16x16x32_f16 v[84:87], v[202:205], v[206:209], v[84:87]
	ds_read_b128 v[60:63], v136 offset:38912
	s_waitcnt vmcnt(7)
	ds_write_b128 v101, v[28:31] offset:16384
	v_mfma_f32_16x16x32_f16 v[72:75], v[210:213], v[190:193], v[72:75]
	s_waitcnt vmcnt(6)
	ds_write_b128 v131, v[16:19] offset:16384
	v_mfma_f32_16x16x32_f16 v[92:95], v[120:123], v[190:193], v[92:95]
	s_waitcnt vmcnt(5)
	ds_write_b128 v132, v[20:23] offset:16384
	v_mfma_f32_16x16x32_f16 v[80:83], v[210:213], v[198:201], v[80:83]
	s_waitcnt vmcnt(4)
	ds_write_b128 v130, v[24:27] offset:16384
	v_mfma_f32_16x16x32_f16 v[88:91], v[210:213], v[206:209], v[88:91]
	s_waitcnt vmcnt(3)
	ds_write_b128 v101, v[4:7] offset:49152
	v_mfma_f32_16x16x32_f16 v[116:119], v[120:123], v[198:201], v[116:119]
	s_waitcnt vmcnt(2)
	ds_write_b128 v131, v[8:11] offset:49152
	v_mfma_f32_16x16x32_f16 v[68:71], v[120:123], v[206:209], v[68:71]
	s_waitcnt vmcnt(1)
	ds_write_b128 v132, v[12:15] offset:49152
	s_waitcnt lgkmcnt(13)
	v_mfma_f32_16x16x32_f16 v[120:123], v[36:39], v[32:35], v[138:141]
	s_waitcnt vmcnt(0)
	ds_write_b128 v130, v[0:3] offset:49152
	s_waitcnt lgkmcnt(12)
	v_mfma_f32_16x16x32_f16 v[138:141], v[44:47], v[32:35], v[142:145]
	s_waitcnt lgkmcnt(10)
	v_mfma_f32_16x16x32_f16 v[142:145], v[52:55], v[32:35], v[154:157]
	s_waitcnt lgkmcnt(8)
	v_mfma_f32_16x16x32_f16 v[32:35], v[60:63], v[32:35], v[64:67]
	v_mfma_f32_16x16x32_f16 v[64:67], v[36:39], v[40:43], v[92:95]
	ds_read_b128 v[154:157], v134 offset:6144
	v_mfma_f32_16x16x32_f16 v[92:95], v[44:47], v[40:43], v[108:111]
	v_mfma_f32_16x16x32_f16 v[108:111], v[52:55], v[40:43], v[112:115]
	v_mfma_f32_16x16x32_f16 v[40:43], v[60:63], v[40:43], v[72:75]
	v_mfma_f32_16x16x32_f16 v[72:75], v[36:39], v[48:51], v[116:119]
	v_mfma_f32_16x16x32_f16 v[36:39], v[36:39], v[56:59], v[68:71]
	s_nop 2
	ds_read_b128 v[68:71], v135 offset:32768
	v_mfma_f32_16x16x32_f16 v[112:115], v[44:47], v[48:51], v[158:161]
	s_nop 2
	ds_read_b128 v[158:161], v135 offset:38912
	v_mfma_f32_16x16x32_f16 v[44:47], v[44:47], v[56:59], v[76:79]
	s_nop 2
	ds_read_b128 v[76:79], v134 offset:2048
	v_mfma_f32_16x16x32_f16 v[116:119], v[52:55], v[48:51], v[162:165]
	v_mfma_f32_16x16x32_f16 v[52:55], v[52:55], v[56:59], v[84:87]
	s_nop 2
	ds_read_b128 v[84:87], v134 offset:4096
	v_mfma_f32_16x16x32_f16 v[48:51], v[60:63], v[48:51], v[80:83]
	s_nop 2
	ds_read_b128 v[80:83], v135 offset:34816
	v_mfma_f32_16x16x32_f16 v[56:59], v[60:63], v[56:59], v[88:91]
	ds_read_b128 v[60:63], v134
	s_waitcnt lgkmcnt(0)
	v_mfma_f32_16x16x32_f16 v[120:123], v[68:71], v[60:63], v[120:123]
	ds_read_b128 v[88:91], v135 offset:36864
	s_waitcnt lgkmcnt(0)
	s_barrier
	v_mfma_f32_16x16x32_f16 v[138:141], v[80:83], v[60:63], v[138:141]
	ds_read_b128 v[0:3], v133 offset:16384
	v_mfma_f32_16x16x32_f16 v[142:145], v[88:91], v[60:63], v[142:145]
	v_mfma_f32_16x16x32_f16 v[32:35], v[158:161], v[60:63], v[32:35]
	v_mfma_f32_16x16x32_f16 v[60:63], v[68:71], v[76:79], v[64:67]
	v_mfma_f32_16x16x32_f16 v[64:67], v[80:83], v[76:79], v[92:95]
	ds_read_b128 v[4:7], v136 offset:49152
	ds_read_b128 v[8:11], v133 offset:18432
	v_mfma_f32_16x16x32_f16 v[92:95], v[88:91], v[76:79], v[108:111]
	ds_read_b128 v[12:15], v136 offset:51200
	v_mfma_f32_16x16x32_f16 v[40:43], v[158:161], v[76:79], v[40:43]
	v_mfma_f32_16x16x32_f16 v[76:79], v[80:83], v[84:87], v[112:115]
	ds_read_b128 v[16:19], v133 offset:20480
	v_mfma_f32_16x16x32_f16 v[44:47], v[80:83], v[154:157], v[44:47]
	ds_read_b128 v[20:23], v136 offset:53248
	v_mfma_f32_16x16x32_f16 v[108:111], v[88:91], v[84:87], v[116:119]
	ds_read_b128 v[24:27], v133 offset:22528
	v_mfma_f32_16x16x32_f16 v[52:55], v[88:91], v[154:157], v[52:55]
	ds_read_b128 v[28:31], v136 offset:55296
	ds_read_b128 v[112:115], v135 offset:53248
	ds_read_b128 v[116:119], v134 offset:22528
	v_ashrrev_i32_e32 v101, 31, v100
	v_mfma_f32_16x16x32_f16 v[48:51], v[158:161], v[84:87], v[48:51]
	v_mfma_f32_16x16x32_f16 v[56:59], v[158:161], v[154:157], v[56:59]
	v_mfma_f32_16x16x32_f16 v[72:75], v[68:71], v[84:87], v[72:75]
	v_mfma_f32_16x16x32_f16 v[36:39], v[68:71], v[154:157], v[36:39]
	s_waitcnt lgkmcnt(8)
	v_mfma_f32_16x16x32_f16 v[68:71], v[4:7], v[0:3], v[120:123]
	s_nop 2
	ds_read_b128 v[120:123], v135 offset:55296
	s_waitcnt lgkmcnt(7)
	v_mfma_f32_16x16x32_f16 v[80:83], v[12:15], v[0:3], v[138:141]
	s_waitcnt lgkmcnt(5)
	v_mfma_f32_16x16x32_f16 v[84:87], v[20:23], v[0:3], v[142:145]
	s_waitcnt lgkmcnt(3)
	v_mfma_f32_16x16x32_f16 v[0:3], v[28:31], v[0:3], v[32:35]
	v_mfma_f32_16x16x32_f16 v[32:35], v[4:7], v[8:11], v[60:63]
	v_mfma_f32_16x16x32_f16 v[60:63], v[12:15], v[8:11], v[64:67]
	v_mfma_f32_16x16x32_f16 v[72:75], v[4:7], v[16:19], v[72:75]
	v_mfma_f32_16x16x32_f16 v[76:79], v[12:15], v[16:19], v[76:79]
	v_mfma_f32_16x16x32_f16 v[44:47], v[12:15], v[24:27], v[44:47]
	ds_read_b128 v[12:15], v134 offset:16384
	v_mfma_f32_16x16x32_f16 v[64:67], v[20:23], v[8:11], v[92:95]
	s_nop 2
	ds_read_b128 v[92:95], v135 offset:51200
	v_mfma_f32_16x16x32_f16 v[88:91], v[20:23], v[16:19], v[108:111]
	s_nop 2
	ds_read_b128 v[108:111], v134 offset:20480
	v_mfma_f32_16x16x32_f16 v[16:19], v[28:31], v[16:19], v[48:51]
	v_mfma_f32_16x16x32_f16 v[48:51], v[20:23], v[24:27], v[52:55]
	ds_read_b128 v[20:23], v134 offset:18432
	v_mfma_f32_16x16x32_f16 v[52:55], v[28:31], v[24:27], v[56:59]
	s_nop 2
	ds_read_b128 v[56:59], v135 offset:49152
	s_waitcnt lgkmcnt(0)
	s_barrier
; DI unsigned pack2(float lo, float hi) { f2_t v = {lo, hi}; h2_t b = __builtin_convertvector(v, h2_t); return __builtin_bit_cast(unsigned, b); }
; template <int VAR> DI void phase_up(const Params& P, int l, char* smem) {
;     ...
; #pragma unroll
;     for (int mt = 0; mt < 4; ++mt) {
;       const int row = row0 + mt * 16 + lr;
; #pragma unroll
;       for (int nt = 0; nt < 4; ++nt) {
;         float v[4];
; #pragma unroll
;         for (int j = 0; j < 4; ++j) { const float a = fmaxf(acc[mt][nt][j] * rs[mt], 0.f); v[j] = a * a; }
;         *(uint2*)(U + (size_t)row * DFF + col0 + nt * 16 + 4 * g) = make_uint2(pack2(v[0], v[1]), pack2(v[2], v[3]));
;       }
;     }
	s_setprio 0
	v_readlane_b32 s60, v255, 0
	v_readlane_b32 s61, v255, 1
	v_readlane_b32 s62, v255, 2
	v_readlane_b32 s63, v255, 3
	v_readlane_b32 s64, v255, 4
	v_readlane_b32 s65, v255, 5
	v_readlane_b32 s66, v255, 6
	v_readlane_b32 s67, v255, 7
	v_readlane_b32 s68, v255, 8
	v_readlane_b32 s69, v255, 9
	v_readlane_b32 s70, v255, 10
	v_readlane_b32 s71, v255, 11
	v_readlane_b32 s72, v255, 12
	v_readlane_b32 s73, v255, 13
	v_readlane_b32 s74, v255, 14
	v_readlane_b32 s75, v255, 15
	s_nop 4
	v_mfma_f32_16x16x32_f16 v[4:7], v[4:7], v[24:27], v[36:39]
	v_mfma_f32_16x16x32_f16 v[68:71], v[56:59], v[12:15], v[68:71]
	v_mfma_f32_16x16x32_f16 v[8:11], v[28:31], v[8:11], v[40:43]
	v_mfma_f32_16x16x32_f16 v[80:83], v[92:95], v[12:15], v[80:83]
	v_mfma_f32_16x16x32_f16 v[84:87], v[112:115], v[12:15], v[84:87]
	v_mfma_f32_16x16x32_f16 v[130:133], v[120:123], v[12:15], v[0:3]
	v_mfma_f32_16x16x32_f16 v[12:15], v[56:59], v[116:119], v[4:7]
	v_mfma_f32_16x16x32_f16 v[4:7], v[112:115], v[116:119], v[48:51]
	s_nop 2
	v_mul_f32_e32 v48, v128, v68
	v_mul_f32_e32 v49, v128, v69
	v_mul_f32_e32 v50, v128, v70
	v_mul_f32_e32 v51, v128, v71
	v_max_f32_e32 v48, 0, v48
	v_max_f32_e32 v49, 0, v49
	v_max_f32_e32 v50, 0, v50
	v_max_f32_e32 v51, 0, v51
	v_mfma_f32_16x16x32_f16 v[134:137], v[56:59], v[20:23], v[32:35]
	v_mul_f32_e64 v48, v48, v48
	v_mul_f32_e64 v49, v49, v49
	v_pk_mul_f32 v[50:51], v[50:51], v[50:51]
	v_cvt_pk_f16_f32 v48, v48, v49
	v_mfma_f32_16x16x32_f16 v[32:35], v[120:123], v[20:23], v[8:11]
	v_cvt_pk_f16_f32 v49, v50, v51
	v_mul_f32_e32 v50, v128, v82
	v_mul_f32_e32 v51, v128, v83
	v_mfma_f32_16x16x32_f16 v[8:11], v[92:95], v[116:119], v[44:47]
	v_max_f32_e32 v50, 0, v50
	v_max_f32_e32 v51, 0, v51
	v_pk_mul_f32 v[50:51], v[50:51], v[50:51]
	v_lshl_add_u64 v[44:45], v[100:101], 1, v[96:97]
	v_lshlrev_b64 v[46:47], 13, v[102:103]
	v_lshl_add_u64 v[46:47], v[44:45], 0, v[46:47]
	global_store_dwordx2 v[46:47], v[48:49], off
	v_mul_f32_e32 v48, v128, v80
	v_mul_f32_e32 v49, v128, v81
	v_max_f32_e32 v48, 0, v48
	v_max_f32_e32 v49, 0, v49
	v_pk_mul_f32 v[48:49], v[48:49], v[48:49]
	v_mfma_f32_16x16x32_f16 v[16:19], v[120:123], v[108:111], v[16:19]
	v_cvt_pk_f16_f32 v48, v48, v49
	v_cvt_pk_f16_f32 v49, v50, v51
	global_store_dwordx2 v[46:47], v[48:49], off offset:32
	v_mul_f32_e32 v48, v128, v84
	v_mul_f32_e32 v49, v128, v85
	v_mul_f32_e32 v50, v128, v86
	v_mul_f32_e32 v51, v128, v87
	v_max_f32_e32 v48, 0, v48
	v_max_f32_e32 v49, 0, v49
	v_max_f32_e32 v50, 0, v50
	v_max_f32_e32 v51, 0, v51
	v_pk_mul_f32 v[48:49], v[48:49], v[48:49]
	v_pk_mul_f32 v[50:51], v[50:51], v[50:51]
	v_cvt_pk_f16_f32 v48, v48, v49
	v_cvt_pk_f16_f32 v49, v50, v51
	global_store_dwordx2 v[46:47], v[48:49], off offset:64
	v_mul_f32_e32 v48, v128, v130
	v_mul_f32_e32 v49, v128, v131
	v_mul_f32_e32 v50, v128, v132
	v_mul_f32_e32 v51, v128, v133
	v_max_f32_e32 v48, 0, v48
	v_max_f32_e32 v49, 0, v49
	v_max_f32_e32 v50, 0, v50
	v_max_f32_e32 v51, 0, v51
	v_mfma_f32_16x16x32_f16 v[40:43], v[92:95], v[20:23], v[60:63]
	v_mul_f32_e64 v48, v48, v48
	v_mul_f32_e64 v49, v49, v49
	v_pk_mul_f32 v[50:51], v[50:51], v[50:51]
	v_mul_f32_e32 v32, v126, v32
	v_mfma_f32_16x16x32_f16 v[36:39], v[112:115], v[20:23], v[64:67]
	v_mul_f32_e32 v33, v126, v33
	v_mul_f32_e32 v34, v126, v34
	v_mul_f32_e32 v35, v126, v35
	v_mfma_f32_16x16x32_f16 v[28:31], v[56:59], v[108:111], v[72:75]
	v_cvt_pk_f16_f32 v48, v48, v49
	v_cvt_pk_f16_f32 v49, v50, v51
	v_max_f32_e32 v32, 0, v32
	v_mfma_f32_16x16x32_f16 v[24:27], v[92:95], v[108:111], v[76:79]
	v_max_f32_e32 v33, 0, v33
	v_max_f32_e32 v34, 0, v34
	v_max_f32_e32 v35, 0, v35
	v_mfma_f32_16x16x32_f16 v[20:23], v[112:115], v[108:111], v[88:91]
	global_store_dwordx2 v[46:47], v[48:49], off offset:96
	v_lshlrev_b64 v[46:47], 13, v[98:99]
	v_pk_mul_f32 v[32:33], v[32:33], v[32:33]
	v_mfma_f32_16x16x32_f16 v[0:3], v[120:123], v[116:119], v[52:55]
	v_mul_f32_e64 v34, v34, v34
	v_mul_f32_e64 v35, v35, v35
	v_mul_f32_e32 v16, v129, v16
	v_mul_f32_e32 v17, v129, v17
	v_mul_f32_e32 v18, v129, v18
	v_mul_f32_e32 v19, v129, v19
	v_lshl_add_u64 v[46:47], v[44:45], 0, v[46:47]
	v_cvt_pk_f16_f32 v32, v32, v33
	v_cvt_pk_f16_f32 v33, v34, v35
	v_max_f32_e32 v16, 0, v16
	v_max_f32_e32 v17, 0, v17
	v_max_f32_e32 v18, 0, v18
	v_max_f32_e32 v19, 0, v19
	v_mul_f32_e32 v48, v126, v134
	v_mul_f32_e32 v49, v126, v135
	v_mul_f32_e32 v50, v126, v136
	v_mul_f32_e32 v51, v126, v137
	v_mul_f32_e32 v40, v126, v40
	v_mul_f32_e32 v41, v126, v41
	v_mul_f32_e32 v42, v126, v42
; DI unsigned pack2(float lo, float hi) { f2_t v = {lo, hi}; h2_t b = __builtin_convertvector(v, h2_t); return __builtin_bit_cast(unsigned, b); }
; template <int VAR> DI void phase_up(const Params& P, int l, char* smem) {
;     ...
; #pragma unroll
;     for (int mt = 0; mt < 4; ++mt) {
;       const int row = row0 + mt * 16 + lr;
; #pragma unroll
;       for (int nt = 0; nt < 4; ++nt) {
;         float v[4];
; #pragma unroll
;         for (int j = 0; j < 4; ++j) { const float a = fmaxf(acc[mt][nt][j] * rs[mt], 0.f); v[j] = a * a; }
;         *(uint2*)(U + (size_t)row * DFF + col0 + nt * 16 + 4 * g) = make_uint2(pack2(v[0], v[1]), pack2(v[2], v[3]));
;       }
;     }
	v_mul_f32_e32 v43, v126, v43
	v_mul_f32_e32 v36, v126, v36
	v_mul_f32_e32 v37, v126, v37
	v_mul_f32_e32 v38, v126, v38
	v_mul_f32_e32 v39, v126, v39
	global_store_dwordx2 v[46:47], v[32:33], off offset:96
	v_lshlrev_b64 v[32:33], 13, v[106:107]
	v_mul_f32_e32 v28, v129, v28
	v_mul_f32_e32 v29, v129, v29
	v_mul_f32_e32 v30, v129, v30
	v_mul_f32_e32 v31, v129, v31
	v_mul_f32_e32 v24, v129, v24
	v_mul_f32_e32 v25, v129, v25
	v_mul_f32_e32 v26, v129, v26
	v_mul_f32_e32 v27, v129, v27
	v_mul_f32_e32 v20, v129, v20
	v_mul_f32_e32 v21, v129, v21
	v_mul_f32_e32 v22, v129, v22
	v_mul_f32_e32 v23, v129, v23
	v_pk_mul_f32 v[16:17], v[16:17], v[16:17]
	v_pk_mul_f32 v[18:19], v[18:19], v[18:19]
	v_mul_f32_e32 v12, v127, v12
	v_mul_f32_e32 v13, v127, v13
	v_mul_f32_e32 v14, v127, v14
	v_mul_f32_e32 v15, v127, v15
	v_mul_f32_e32 v8, v127, v8
	v_mul_f32_e32 v9, v127, v9
	v_mul_f32_e32 v10, v127, v10
	v_mul_f32_e32 v11, v127, v11
	v_mul_f32_e32 v4, v127, v4
	v_mul_f32_e32 v5, v127, v5
	v_mul_f32_e32 v6, v127, v6
	v_mul_f32_e32 v7, v127, v7
	v_mul_f32_e32 v0, v127, v0
	v_mul_f32_e32 v1, v127, v1
	v_mul_f32_e32 v2, v127, v2
	v_mul_f32_e32 v3, v127, v3
	v_max_f32_e32 v48, 0, v48
	v_max_f32_e32 v49, 0, v49
	v_max_f32_e32 v50, 0, v50
	v_max_f32_e32 v51, 0, v51
	v_max_f32_e32 v40, 0, v40
	v_max_f32_e32 v41, 0, v41
	v_max_f32_e32 v42, 0, v42
	v_max_f32_e32 v43, 0, v43
	v_max_f32_e32 v36, 0, v36
	v_max_f32_e32 v37, 0, v37
	v_max_f32_e32 v38, 0, v38
	v_max_f32_e32 v39, 0, v39
	v_lshl_add_u64 v[32:33], v[44:45], 0, v[32:33]
	v_max_f32_e32 v28, 0, v28
	v_max_f32_e32 v29, 0, v29
	v_max_f32_e32 v30, 0, v30
	v_max_f32_e32 v31, 0, v31
	v_max_f32_e32 v24, 0, v24
	v_max_f32_e32 v25, 0, v25
	v_max_f32_e32 v26, 0, v26
	v_max_f32_e32 v27, 0, v27
	v_max_f32_e32 v20, 0, v20
	v_max_f32_e32 v21, 0, v21
	v_max_f32_e32 v22, 0, v22
	v_max_f32_e32 v23, 0, v23
	v_cvt_pk_f16_f32 v16, v16, v17
	v_cvt_pk_f16_f32 v17, v18, v19
	v_max_f32_e32 v12, 0, v12
	v_max_f32_e32 v13, 0, v13
	v_max_f32_e32 v14, 0, v14
	v_max_f32_e32 v15, 0, v15
	v_max_f32_e32 v8, 0, v8
	v_max_f32_e32 v9, 0, v9
	v_max_f32_e32 v10, 0, v10
	v_max_f32_e32 v11, 0, v11
	v_max_f32_e32 v4, 0, v4
	v_max_f32_e32 v5, 0, v5
	v_max_f32_e32 v6, 0, v6
	v_max_f32_e32 v7, 0, v7
	v_max_f32_e32 v0, 0, v0
	v_max_f32_e32 v1, 0, v1
	v_max_f32_e32 v2, 0, v2
	v_max_f32_e32 v3, 0, v3
	v_pk_mul_f32 v[48:49], v[48:49], v[48:49]
	v_pk_mul_f32 v[50:51], v[50:51], v[50:51]
	v_pk_mul_f32 v[40:41], v[40:41], v[40:41]
	v_pk_mul_f32 v[42:43], v[42:43], v[42:43]
	v_pk_mul_f32 v[36:37], v[36:37], v[36:37]
	v_pk_mul_f32 v[38:39], v[38:39], v[38:39]
	v_pk_mul_f32 v[28:29], v[28:29], v[28:29]
	v_pk_mul_f32 v[30:31], v[30:31], v[30:31]
	v_pk_mul_f32 v[24:25], v[24:25], v[24:25]
	v_pk_mul_f32 v[26:27], v[26:27], v[26:27]
	v_pk_mul_f32 v[20:21], v[20:21], v[20:21]
	v_pk_mul_f32 v[22:23], v[22:23], v[22:23]
	global_store_dwordx2 v[32:33], v[16:17], off offset:96
	v_lshlrev_b64 v[16:17], 13, v[104:105]
	v_pk_mul_f32 v[12:13], v[12:13], v[12:13]
	v_pk_mul_f32 v[14:15], v[14:15], v[14:15]
	v_pk_mul_f32 v[8:9], v[8:9], v[8:9]
	v_pk_mul_f32 v[10:11], v[10:11], v[10:11]
	v_pk_mul_f32 v[4:5], v[4:5], v[4:5]
	v_pk_mul_f32 v[6:7], v[6:7], v[6:7]
	v_pk_mul_f32 v[0:1], v[0:1], v[0:1]
	v_pk_mul_f32 v[2:3], v[2:3], v[2:3]
	v_cvt_pk_f16_f32 v48, v48, v49
	v_cvt_pk_f16_f32 v49, v50, v51
	v_cvt_pk_f16_f32 v40, v40, v41
	v_cvt_pk_f16_f32 v41, v42, v43
	v_cvt_pk_f16_f32 v36, v36, v37
	v_cvt_pk_f16_f32 v37, v38, v39
	v_cvt_pk_f16_f32 v28, v28, v29
	v_cvt_pk_f16_f32 v29, v30, v31
	v_cvt_pk_f16_f32 v24, v24, v25
	v_cvt_pk_f16_f32 v25, v26, v27
	v_cvt_pk_f16_f32 v20, v20, v21
	v_cvt_pk_f16_f32 v21, v22, v23
	v_lshl_add_u64 v[16:17], v[44:45], 0, v[16:17]
	v_cvt_pk_f16_f32 v12, v12, v13
	v_cvt_pk_f16_f32 v13, v14, v15
	v_cvt_pk_f16_f32 v8, v8, v9
	v_cvt_pk_f16_f32 v9, v10, v11
	v_cvt_pk_f16_f32 v4, v4, v5
	v_cvt_pk_f16_f32 v5, v6, v7
	v_cvt_pk_f16_f32 v0, v0, v1
	v_cvt_pk_f16_f32 v1, v2, v3
	global_store_dwordx2 v[46:47], v[48:49], off
	global_store_dwordx2 v[46:47], v[40:41], off offset:32
	global_store_dwordx2 v[46:47], v[36:37], off offset:64
	global_store_dwordx2 v[32:33], v[28:29], off
	global_store_dwordx2 v[32:33], v[24:25], off offset:32
	global_store_dwordx2 v[32:33], v[20:21], off offset:64
	global_store_dwordx2 v[16:17], v[12:13], off
	global_store_dwordx2 v[16:17], v[8:9], off offset:32
	global_store_dwordx2 v[16:17], v[4:5], off offset:64
	global_store_dwordx2 v[16:17], v[0:1], off offset:96
	s_branch .LBB0_1312

; #define LAS __attribute__((address_space(3)))
; __global__ void __launch_bounds__(256, 2) fwd_megakernel(Params P) {
;   __shared__ __attribute__((aligned(16))) char smem[SMEM_TOTAL];
;   __shared__ uint4 xb_words;
;   cg::grid_group grid = cg::this_grid();
;   if (threadIdx.x == 0) xb_words = make_uint4(0u, 0u, 0u, 0u);
;   __syncthreads();
;   const XcdBarrier xb = xcd_barrier_post((unsigned*)(P.ws + OFF_BAR), (volatile LAS unsigned*)&xb_words);
	.amdhsa_kernel _Z14fwd_megakernel6Params
		.amdhsa_group_segment_fixed_size 74064
		.amdhsa_private_segment_fixed_size 0
		.amdhsa_kernarg_size 592
		.amdhsa_user_sgpr_count 2
		.amdhsa_user_sgpr_dispatch_ptr 0
		.amdhsa_user_sgpr_queue_ptr 0
		.amdhsa_user_sgpr_kernarg_segment_ptr 1
		.amdhsa_user_sgpr_dispatch_id 0
		.amdhsa_user_sgpr_kernarg_preload_length 0
		.amdhsa_user_sgpr_kernarg_preload_offset 0
		.amdhsa_user_sgpr_private_segment_size 0
		.amdhsa_uses_dynamic_stack 0
		.amdhsa_enable_private_segment 0
		.amdhsa_system_sgpr_workgroup_id_x 1
		.amdhsa_system_sgpr_workgroup_id_y 0
		.amdhsa_system_sgpr_workgroup_id_z 0
		.amdhsa_system_sgpr_workgroup_info 0
		.amdhsa_system_vgpr_workitem_id 2
		.amdhsa_next_free_vgpr 256
		.amdhsa_next_free_sgpr 102
		.amdhsa_accum_offset 256
		.amdhsa_reserve_vcc 1
		.amdhsa_float_round_mode_32 0
		.amdhsa_float_round_mode_16_64 0
		.amdhsa_float_denorm_mode_32 3
		.amdhsa_float_denorm_mode_16_64 3
		.amdhsa_dx10_clamp 1
		.amdhsa_ieee_mode 1
		.amdhsa_fp16_overflow 0
		.amdhsa_tg_split 0
		.amdhsa_exception_fp_ieee_invalid_op 0
		.amdhsa_exception_fp_denorm_src 0
		.amdhsa_exception_fp_ieee_div_zero 0
		.amdhsa_exception_fp_ieee_overflow 0
		.amdhsa_exception_fp_ieee_underflow 0
		.amdhsa_exception_fp_ieee_inexact 0
		.amdhsa_exception_int_div_zero 0
	.end_amdhsa_kernel

; __global__ void __launch_bounds__(256, 2) fwd_megakernel(Params P) {
;   __shared__ __attribute__((aligned(16))) char smem[SMEM_TOTAL];
;   __shared__ uint4 xb_words;
amdhsa.kernels:
  - .agpr_count:     0
    .args:
      - .offset:         0
        .size:           336
        .value_kind:     by_value
      - .offset:         336
        .size:           4
        .value_kind:     hidden_block_count_x
      - .offset:         340
        .size:           4
        .value_kind:     hidden_block_count_y
      - .offset:         344
        .size:           4
        .value_kind:     hidden_block_count_z
      - .offset:         348
        .size:           2
        .value_kind:     hidden_group_size_x
      - .offset:         350
        .size:           2
        .value_kind:     hidden_group_size_y
      - .offset:         352
        .size:           2
        .value_kind:     hidden_group_size_z
      - .offset:         354
        .size:           2
        .value_kind:     hidden_remainder_x
      - .offset:         356
        .size:           2
        .value_kind:     hidden_remainder_y
      - .offset:         358
        .size:           2
        .value_kind:     hidden_remainder_z
      - .offset:         376
        .size:           8
        .value_kind:     hidden_global_offset_x
      - .offset:         384
        .size:           8
        .value_kind:     hidden_global_offset_y
      - .offset:         392
        .size:           8
        .value_kind:     hidden_global_offset_z
      - .offset:         400
        .size:           2
        .value_kind:     hidden_grid_dims
      - .offset:         424
        .size:           8
        .value_kind:     hidden_multigrid_sync_arg
    .group_segment_fixed_size: 74064
    .kernarg_segment_align: 8
    .kernarg_segment_size: 592
    .language:       OpenCL C
    .language_version:
      - 2
      - 0
    .max_flat_workgroup_size: 256
    .name:           _Z14fwd_megakernel6Params
    .private_segment_fixed_size: 0
    .sgpr_count:     108
    .sgpr_spill_count: 170
    .symbol:         _Z14fwd_megakernel6Params.kd
    .uniform_work_group_size: 1
    .uses_dynamic_stack: false
    .vgpr_count:     256
    .vgpr_spill_count: 0
    .wavefront_size: 64
